# cross-attention V chunks 1-6: output conversion/staging of chunk c runs after the barrier and first fragment reads of chunk c+1 (image writes moved up, vmcnt re-derived)
# baseline (speedup 1.0000x reference)
; #define XLAS __attribute__((address_space(3)))
; __device__ __forceinline__ void unit(XLAS unsigned char* lds, const bf16_t* Qg, const bf16_t* Kg, const bf16_t* Vg, bf16_t* Og) {
;     int tid_ = threadIdx.x; asm volatile("" : "+v"(tid_)); const int tid = tid_, lane = tid & 63, r32 = lane & 31, hi = lane >> 5; const int wid = __builtin_amdgcn_readfirstlane(tid >> 6);
;     const int sr = tid >> 4, sseg = tid & 15;
;     const bf16_t* kgp = Kg + (size_t)sr * 4096 + sseg * 16;
;     const bf16_t* vgp = Vg + (size_t)sr * 4096 + sseg * 16;
;     const unsigned wofs = (unsigned)(sr * KP + sseg * 32);
;     ...
;     u32x4 g[2][2];
;     g[0][0] = *(const u32x4*)(XAT_SRC(0)); g[0][1] = *(const u32x4*)(XAT_SRC(0) + 8); g[1][0] = *(const u32x4*)(XAT_SRC(1)); g[1][1] = *(const u32x4*)(XAT_SRC(1) + 8);
;     XLAS unsigned char* xs = lds + XS_OFF + wid * XS_BYTES;
;     bf16x8 qf[16];
; #pragma unroll
;     for (int hq = 0; hq < 2; ++hq) {
;         const bf16_t* qbase = Qg + (size_t)(wid * 32 + (lane >> 4)) * 1024 + hq * 128 + (lane & 15) * 8;
;         u32x4 qv[8];
; #pragma unroll
;         for (int i = 0; i < 8; ++i) qv[i] = *(const u32x4*)(qbase + (size_t)(4 * i) * 1024);
; #pragma unroll
;         for (int i = 0; i < 8; ++i) *(XLAS u32x4*)(xs + (4 * i + (lane >> 4)) * 272 + (lane & 15) * 16) = qv[i];
; #pragma unroll
;         for (int s = 0; s < 8; ++s) qf[hq * 8 + s] = *(const XLAS bf16x8*)(xs + r32 * 272 + s * 32 + hi * 16);
;     }
;     const int krow = (r32 & 0x13) | ((r32 & 4) << 1) | ((r32 & 8) >> 1);
;     const unsigned kro = (unsigned)(krow * KP + hi * 16), vro = (unsigned)(r32 * KP + hi * 16);
;     f32x16 S[8];
; #pragma unroll
;     for (int c = 0; c < 8; ++c) {
;         XLAS unsigned char* buf = lds + (c & 1) * CHB;
;         *(XLAS u32x4*)(buf + wofs) = g[c & 1][0]; *(XLAS u32x4*)(buf + wofs + 16) = g[c & 1][1];
;         __syncthreads();
; __global__ void __launch_bounds__(NWAVES * 64, 2) trunk_fwd(Args args) {
;     ...
;                 for (int i = 0; S.next(i, xu); ++i) { const int tm = xu.pm, h = xu.pn, b = tm >> 4;
;     ...
;                     xat::unit(L, BIG + (size_t)tm * 256 * 1024 + h * 256, KB + (size_t)b * 256 * 4096 + l * 1024 + h * 256, VT + (size_t)(l * 1024 + h * 256) * 4096 + b * 256, MIX + (size_t)tm * 256 * 1024 + h * 256);
.LBB0_589:
	s_ashr_i32 s67, s66, 31
	s_ashr_i32 s4, s66, 4
	s_lshl_b64 s[26:27], s[66:67], 19
	s_add_u32 s5, s52, s26
	v_readlane_b32 s8, v255, 39
	s_addc_u32 s16, s53, s27
	s_lshl_b32 s8, s8, 8
	s_ashr_i32 s9, s8, 31
	s_lshl_b64 s[28:29], s[8:9], 1
	s_add_u32 s54, s5, s28
	s_addc_u32 s55, s16, s29
	s_ashr_i32 s5, s4, 31
	s_lshl_b64 s[16:17], s[4:5], 21
	s_add_u32 s5, s3, s16
	s_addc_u32 s9, s7, s17
	s_add_u32 s16, s5, s28
	s_addc_u32 s17, s9, s29
	s_add_i32 s8, s8, s6
	s_ashr_i32 s9, s8, 31
	s_lshl_b64 s[8:9], s[8:9], 13
	s_add_u32 s8, s86, s8
	s_addc_u32 s9, s87, s9
	s_lshl_b32 s4, s4, 8
	s_ashr_i32 s5, s4, 31
	s_lshl_b64 s[4:5], s[4:5], 1
	s_add_u32 s8, s8, s4
	s_addc_u32 s9, s9, s5
	s_add_u32 s4, s50, s26
	s_addc_u32 s5, s51, s27
	v_mov_b32_e32 v215, v206
	s_add_u32 s4, s4, s28
	s_addc_u32 s5, s5, s29
	v_readfirstlane_b32 s26, v215
	s_ashr_i32 s27, s26, 6
	s_lshl_b32 s26, s27, 5
	v_bfe_u32 v90, v215, 4, 2
	v_or_b32_e32 v2, s26, v90
	v_ashrrev_i32_e32 v3, 31, v2
	v_and_b32_e32 v80, 15, v215
	v_lshlrev_b64 v[2:3], 11, v[2:3]
	v_lshlrev_b32_e32 v0, 4, v80
	v_lshl_add_u64 v[2:3], s[54:55], 0, v[2:3]
	v_lshl_add_u64 v[6:7], v[2:3], 0, v[0:1]
	v_add_co_u32_e32 v8, vcc, s33, v6
	s_movk_i32 s28, 0x4000
	s_nop 0
	v_addc_co_u32_e32 v9, vcc, 0, v7, vcc
	v_add_co_u32_e32 v10, vcc, s28, v6
	s_mov_b32 s29, 0x8000
	s_nop 0
	v_addc_co_u32_e32 v11, vcc, 0, v7, vcc
	v_add_co_u32_e32 v12, vcc, s2, v6
	s_mov_b32 s42, 0xc000
	s_nop 0
	v_addc_co_u32_e32 v13, vcc, 0, v7, vcc
	v_add_co_u32_e32 v14, vcc, s29, v6
	s_mov_b32 s44, 0xe000
	s_nop 0
	v_addc_co_u32_e32 v15, vcc, 0, v7, vcc
	v_add_co_u32_e32 v16, vcc, s1, v6
	v_ashrrev_i32_e32 v88, 4, v215
	s_nop 0
	v_addc_co_u32_e32 v17, vcc, 0, v7, vcc
	v_add_co_u32_e32 v18, vcc, s42, v6
	v_ashrrev_i32_e32 v89, 31, v88
	s_nop 0
	v_addc_co_u32_e32 v19, vcc, 0, v7, vcc
	v_add_co_u32_e32 v76, vcc, s44, v6
	global_load_dwordx4 v[2:5], v[6:7], off
	global_load_dwordx4 v[20:23], v[8:9], off
	v_addc_co_u32_e32 v77, vcc, 0, v7, vcc
	global_load_dwordx4 v[24:27], v[10:11], off
	global_load_dwordx4 v[28:31], v[12:13], off
	global_load_dwordx4 v[32:35], v[14:15], off
	global_load_dwordx4 v[36:39], v[16:17], off
	global_load_dwordx4 v[40:43], v[18:19], off
	global_load_dwordx4 v[44:47], v[76:77], off
	global_load_dwordx4 v[48:51], v[6:7], off offset:256
	global_load_dwordx4 v[52:55], v[8:9], off offset:256
	global_load_dwordx4 v[56:59], v[10:11], off offset:256
	global_load_dwordx4 v[60:63], v[12:13], off offset:256
	global_load_dwordx4 v[64:67], v[14:15], off offset:256
	global_load_dwordx4 v[68:71], v[16:17], off offset:256
	global_load_dwordx4 v[72:75], v[18:19], off offset:256
	s_nop 0
	global_load_dwordx4 v[76:79], v[76:77], off offset:256
	v_lshlrev_b64 v[16:17], 13, v[88:89]
	v_lshl_add_u64 v[6:7], s[16:17], 0, v[16:17]
	v_lshlrev_b32_e32 v18, 5, v80
	v_mov_b32_e32 v19, v1
	v_lshl_add_u64 v[14:15], v[6:7], 0, v[18:19]
	global_load_dwordx4 v[80:83], v[14:15], off
	global_load_dwordx4 v[84:87], v[14:15], off offset:16
	s_mulk_i32 s27, 0x2200
	v_and_b32_e32 v216, 31, v215
	v_bfe_u32 v217, v215, 5, 1
	v_add_co_u32_e32 v8, vcc, s45, v14
	s_add_i32 s16, s27, 0
	v_mul_u32_u24_e32 v90, 0x110, v90
	v_lshl_add_u64 v[6:7], v[14:15], 0, s[22:23]
	v_addc_co_u32_e32 v9, vcc, 0, v15, vcc
	v_mul_u32_u24_e32 v89, 0x110, v216
	v_lshlrev_b32_e32 v218, 4, v217
	v_add3_u32 v0, s16, v0, v90
	global_load_dwordx4 v[10:13], v[8:9], off
	s_nop 0
	global_load_dwordx4 v[6:9], v[6:7], off offset:16
	v_add3_u32 v89, s16, v89, v218
	s_movk_i32 s17, 0x210
	v_lshl_add_u64 v[16:17], s[8:9], 0, v[16:17]
	v_lshl_add_u64 v[212:213], v[16:17], 0, v[18:19]
	s_waitcnt vmcnt(19)
	ds_write_b128 v0, v[2:5] offset:34816
	s_waitcnt vmcnt(18)
	ds_write_b128 v0, v[20:23] offset:35904
	s_waitcnt vmcnt(17)
	ds_write_b128 v0, v[24:27] offset:36992
	s_waitcnt vmcnt(16)
	ds_write_b128 v0, v[28:31] offset:38080
	s_waitcnt vmcnt(15)
	ds_write_b128 v0, v[32:35] offset:39168
	s_waitcnt vmcnt(14)
	ds_write_b128 v0, v[36:39] offset:40256
	s_waitcnt vmcnt(13)
	ds_write_b128 v0, v[40:43] offset:41344
	s_waitcnt vmcnt(12)
	ds_write_b128 v0, v[44:47] offset:42432
	ds_read_b128 v[2:5], v89 offset:34816
	ds_read_b128 v[170:173], v89 offset:34848
	ds_read_b128 v[166:169], v89 offset:34880
	ds_read_b128 v[162:165], v89 offset:34912
	ds_read_b128 v[158:161], v89 offset:34944
	ds_read_b128 v[154:157], v89 offset:34976
	ds_read_b128 v[134:137], v89 offset:35008
	ds_read_b128 v[130:133], v89 offset:35040
	s_waitcnt vmcnt(11)
	ds_write_b128 v0, v[48:51] offset:34816
	s_waitcnt vmcnt(10)
	ds_write_b128 v0, v[52:55] offset:35904
	s_waitcnt vmcnt(9)
	ds_write_b128 v0, v[56:59] offset:36992
	s_waitcnt vmcnt(8)
	ds_write_b128 v0, v[60:63] offset:38080
	s_waitcnt vmcnt(7)
	ds_write_b128 v0, v[64:67] offset:39168
	s_waitcnt vmcnt(6)
	ds_write_b128 v0, v[68:71] offset:40256
	s_waitcnt vmcnt(5)
	ds_write_b128 v0, v[72:75] offset:41344
	s_waitcnt vmcnt(4)
	ds_write_b128 v0, v[76:79] offset:42432
	v_mul_lo_u32 v0, v88, s17
	v_add_co_u32_e32 v22, vcc, s46, v14
	v_add3_u32 v214, v0, v18, 0
	s_nop 0
	v_addc_co_u32_e32 v23, vcc, 0, v15, vcc
	ds_read_b128 v[202:205], v89 offset:34816
	ds_read_b128 v[198:201], v89 offset:34848
	ds_read_b128 v[194:197], v89 offset:34880
	ds_read_b128 v[190:193], v89 offset:34912
	ds_read_b128 v[186:189], v89 offset:34944
	ds_read_b128 v[182:185], v89 offset:34976
	ds_read_b128 v[178:181], v89 offset:35008
	ds_read_b128 v[174:177], v89 offset:35040
	s_waitcnt vmcnt(3)
	ds_write_b128 v214, v[80:83]
	s_waitcnt vmcnt(2)
	ds_write_b128 v214, v[84:87] offset:16
	s_waitcnt lgkmcnt(0)
	s_barrier
; #define XLAS __attribute__((address_space(3)))
; __device__ __forceinline__ void unit(XLAS unsigned char* lds, const bf16_t* Qg, const bf16_t* Kg, const bf16_t* Vg, bf16_t* Og) {
;     ...
;     for (int c = 0; c < 8; ++c) {
;         XLAS unsigned char* buf = lds + (c & 1) * CHB;
;         *(XLAS u32x4*)(buf + wofs) = g[c & 1][0]; *(XLAS u32x4*)(buf + wofs + 16) = g[c & 1][1];
;         __syncthreads();
;         { g[c & 1][0] = *(const u32x4*)(XAT_SRC(c + 2)); g[c & 1][1] = *(const u32x4*)(XAT_SRC(c + 2) + 8); }
;         f32x16 a = {};
;         bf16x8 kfa[4], kfb[4];
; #pragma unroll
;         for (int j = 0; j < 4; ++j) kfa[j] = *(const XLAS bf16x8*)(buf + kro + j * 32);
; #pragma unroll
;         for (int gq = 0; gq < 4; gq += 2) {
; #pragma unroll
;             for (int j = 0; j < 4; ++j) kfb[j] = *(const XLAS bf16x8*)(buf + kro + (4 * gq + 4 + j) * 32);
;             __builtin_amdgcn_sched_barrier(0);
; #pragma unroll
;             for (int j = 0; j < 4; ++j) a = __builtin_amdgcn_mfma_f32_32x32x16_bf16(kfa[j], qf[4 * gq + j], a, 0, 0, 0);
;             if (gq < 2) {
; #pragma unroll
;                 for (int j = 0; j < 4; ++j) kfa[j] = *(const XLAS bf16x8*)(buf + kro + (4 * gq + 8 + j) * 32); }
;             __builtin_amdgcn_sched_barrier(0);
; #pragma unroll
;             for (int j = 0; j < 4; ++j) a = __builtin_amdgcn_mfma_f32_32x32x16_bf16(kfb[j], qf[4 * gq + 4 + j], a, 0, 0, 0);
;         }
;         S[c] = a;
;     }
	v_lshl_add_u64 v[20:21], v[14:15], 0, s[34:35]
	global_load_dwordx4 v[50:53], v[22:23], off
	global_load_dwordx4 v[54:57], v[20:21], off offset:16
	v_lshlrev_b32_e32 v20, 1, v215
	v_lshrrev_b32_e32 v21, 1, v215
	v_and_b32_e32 v0, 19, v215
	v_and_b32_e32 v20, 8, v20
	v_and_b32_e32 v21, 4, v21
	v_or3_b32 v0, v0, v20, v21
	v_mul_u32_u24_e32 v0, 0x210, v0
	v_add3_u32 v0, v0, v218, 0
	ds_read_b128 v[20:23], v0
	ds_read_b128 v[34:37], v0 offset:32
	ds_read_b128 v[38:41], v0 offset:64
	ds_read_b128 v[42:45], v0 offset:96
	ds_read_b128 v[46:49], v0 offset:128
	ds_read_b128 v[58:61], v0 offset:160
	ds_read_b128 v[62:65], v0 offset:192
	ds_read_b128 v[66:69], v0 offset:224
	s_waitcnt lgkmcnt(7)
	v_mfma_f32_32x32x16_bf16 v[18:33], v[20:23], v[2:5], 0
	s_waitcnt lgkmcnt(6)
	v_mfma_f32_32x32x16_bf16 v[18:33], v[34:37], v[170:173], v[18:33]
	s_waitcnt lgkmcnt(5)
	v_mfma_f32_32x32x16_bf16 v[18:33], v[38:41], v[166:169], v[18:33]
	ds_read_b128 v[34:37], v0 offset:352
	ds_read_b128 v[38:41], v0 offset:320
	ds_read_b128 v[70:73], v0 offset:256
	ds_read_b128 v[74:77], v0 offset:288
	s_waitcnt lgkmcnt(8)
	v_mfma_f32_32x32x16_bf16 v[18:33], v[42:45], v[162:165], v[18:33]
	s_waitcnt lgkmcnt(7)
	v_mfma_f32_32x32x16_bf16 v[18:33], v[46:49], v[158:161], v[18:33]
	s_waitcnt lgkmcnt(6)
	v_mfma_f32_32x32x16_bf16 v[18:33], v[58:61], v[154:157], v[18:33]
	s_waitcnt lgkmcnt(5)
	v_mfma_f32_32x32x16_bf16 v[18:33], v[62:65], v[134:137], v[18:33]
	ds_read_b128 v[42:45], v0 offset:384
	ds_read_b128 v[46:49], v0 offset:416
	ds_read_b128 v[58:61], v0 offset:448
	ds_read_b128 v[62:65], v0 offset:480
	s_waitcnt lgkmcnt(8)
	v_mfma_f32_32x32x16_bf16 v[18:33], v[66:69], v[130:133], v[18:33]
	s_waitcnt lgkmcnt(5)
	v_mfma_f32_32x32x16_bf16 v[18:33], v[70:73], v[202:205], v[18:33]
	s_waitcnt lgkmcnt(4)
	v_mfma_f32_32x32x16_bf16 v[18:33], v[74:77], v[198:201], v[18:33]
	v_mfma_f32_32x32x16_bf16 v[18:33], v[38:41], v[194:197], v[18:33]
	v_mfma_f32_32x32x16_bf16 v[18:33], v[34:37], v[190:193], v[18:33]
	s_waitcnt vmcnt(3)
	ds_write_b128 v214, v[10:13] offset:16896
	s_waitcnt vmcnt(2)
	ds_write_b128 v214, v[6:9] offset:16912
	v_add_co_u32_e32 v6, vcc, s47, v14
	v_lshl_add_u64 v[10:11], v[14:15], 0, s[36:37]
	s_nop 0
	v_addc_co_u32_e32 v7, vcc, 0, v15, vcc
	s_waitcnt lgkmcnt(0)
	s_barrier
	global_load_dwordx4 v[6:9], v[6:7], off
	s_nop 0
	global_load_dwordx4 v[10:13], v[10:11], off offset:16
	v_mfma_f32_32x32x16_bf16 v[18:33], v[42:45], v[186:189], v[18:33]
	v_mfma_f32_32x32x16_bf16 v[18:33], v[46:49], v[182:185], v[18:33]
	v_mfma_f32_32x32x16_bf16 v[18:33], v[58:61], v[178:181], v[18:33]
	ds_read_b128 v[34:37], v0 offset:16896
	ds_read_b128 v[58:61], v0 offset:16928
	ds_read_b128 v[66:69], v0 offset:16960
	ds_read_b128 v[70:73], v0 offset:16992
	ds_read_b128 v[74:77], v0 offset:17024
	ds_read_b128 v[78:81], v0 offset:17056
	ds_read_b128 v[82:85], v0 offset:17088
	ds_read_b128 v[86:89], v0 offset:17120
	v_mfma_f32_32x32x16_bf16 v[18:33], v[62:65], v[174:177], v[18:33]
	s_waitcnt lgkmcnt(7)
	v_mfma_f32_32x32x16_bf16 v[34:49], v[34:37], v[2:5], 0
	s_waitcnt lgkmcnt(6)
	v_mfma_f32_32x32x16_bf16 v[34:49], v[58:61], v[170:173], v[34:49]
	s_waitcnt lgkmcnt(5)
	v_mfma_f32_32x32x16_bf16 v[34:49], v[66:69], v[166:169], v[34:49]
	ds_read_b128 v[58:61], v0 offset:17248
	ds_read_b128 v[62:65], v0 offset:17216
	ds_read_b128 v[66:69], v0 offset:17152
	ds_read_b128 v[90:93], v0 offset:17184
	s_waitcnt lgkmcnt(8)
	v_mfma_f32_32x32x16_bf16 v[34:49], v[70:73], v[162:165], v[34:49]
	s_waitcnt lgkmcnt(7)
	v_mfma_f32_32x32x16_bf16 v[34:49], v[74:77], v[158:161], v[34:49]
	s_waitcnt lgkmcnt(6)
	v_mfma_f32_32x32x16_bf16 v[34:49], v[78:81], v[154:157], v[34:49]
	s_waitcnt lgkmcnt(5)
	v_mfma_f32_32x32x16_bf16 v[34:49], v[82:85], v[134:137], v[34:49]
	ds_read_b128 v[70:73], v0 offset:17280
	ds_read_b128 v[74:77], v0 offset:17312
	ds_read_b128 v[78:81], v0 offset:17344
	ds_read_b128 v[82:85], v0 offset:17376
	s_waitcnt lgkmcnt(8)
	v_mfma_f32_32x32x16_bf16 v[34:49], v[86:89], v[130:133], v[34:49]
	s_waitcnt lgkmcnt(5)
	v_mfma_f32_32x32x16_bf16 v[34:49], v[66:69], v[202:205], v[34:49]
	s_waitcnt lgkmcnt(4)
	v_mfma_f32_32x32x16_bf16 v[34:49], v[90:93], v[198:201], v[34:49]
	v_mfma_f32_32x32x16_bf16 v[34:49], v[62:65], v[194:197], v[34:49]
	v_mfma_f32_32x32x16_bf16 v[34:49], v[58:61], v[190:193], v[34:49]
	s_mov_b32 s17, 0x100000
	s_waitcnt vmcnt(3)
	ds_write_b128 v214, v[50:53]
	s_waitcnt vmcnt(2)
	ds_write_b128 v214, v[54:57] offset:16
	v_add_co_u32_e32 v50, vcc, s17, v14
	s_waitcnt lgkmcnt(0)
	s_nop 0
	v_addc_co_u32_e32 v51, vcc, 0, v15, vcc
	s_barrier
; #define XLAS __attribute__((address_space(3)))
; __device__ __forceinline__ void unit(XLAS unsigned char* lds, const bf16_t* Qg, const bf16_t* Kg, const bf16_t* Vg, bf16_t* Og) {
;     ...
;     for (int c = 0; c < 8; ++c) {
;         XLAS unsigned char* buf = lds + (c & 1) * CHB;
;         *(XLAS u32x4*)(buf + wofs) = g[c & 1][0]; *(XLAS u32x4*)(buf + wofs + 16) = g[c & 1][1];
;         __syncthreads();
;         { g[c & 1][0] = *(const u32x4*)(XAT_SRC(c + 2)); g[c & 1][1] = *(const u32x4*)(XAT_SRC(c + 2) + 8); }
;         f32x16 a = {};
;         bf16x8 kfa[4], kfb[4];
; #pragma unroll
;         for (int j = 0; j < 4; ++j) kfa[j] = *(const XLAS bf16x8*)(buf + kro + j * 32);
; #pragma unroll
;         for (int gq = 0; gq < 4; gq += 2) {
; #pragma unroll
;             for (int j = 0; j < 4; ++j) kfb[j] = *(const XLAS bf16x8*)(buf + kro + (4 * gq + 4 + j) * 32);
;             __builtin_amdgcn_sched_barrier(0);
; #pragma unroll
;             for (int j = 0; j < 4; ++j) a = __builtin_amdgcn_mfma_f32_32x32x16_bf16(kfa[j], qf[4 * gq + j], a, 0, 0, 0);
;             if (gq < 2) {
; #pragma unroll
;                 for (int j = 0; j < 4; ++j) kfa[j] = *(const XLAS bf16x8*)(buf + kro + (4 * gq + 8 + j) * 32); }
;             __builtin_amdgcn_sched_barrier(0);
; #pragma unroll
;             for (int j = 0; j < 4; ++j) a = __builtin_amdgcn_mfma_f32_32x32x16_bf16(kfb[j], qf[4 * gq + 4 + j], a, 0, 0, 0);
;         }
;         S[c] = a;
;     }
	v_lshl_add_u64 v[16:17], v[14:15], 0, s[30:31]
	global_load_dwordx4 v[86:89], v[50:51], off
	global_load_dwordx4 v[90:93], v[16:17], off offset:16
	v_mfma_f32_32x32x16_bf16 v[34:49], v[70:73], v[186:189], v[34:49]
	v_mfma_f32_32x32x16_bf16 v[34:49], v[74:77], v[182:185], v[34:49]
	v_mfma_f32_32x32x16_bf16 v[34:49], v[78:81], v[178:181], v[34:49]
	ds_read_b128 v[50:53], v0
	ds_read_b128 v[66:69], v0 offset:32
	ds_read_b128 v[70:73], v0 offset:64
	ds_read_b128 v[74:77], v0 offset:96
	ds_read_b128 v[78:81], v0 offset:128
	ds_read_b128 v[94:97], v0 offset:160
	ds_read_b128 v[98:101], v0 offset:192
	ds_read_b128 v[102:105], v0 offset:224
	v_mfma_f32_32x32x16_bf16 v[34:49], v[82:85], v[174:177], v[34:49]
	s_waitcnt lgkmcnt(7)
	v_mfma_f32_32x32x16_bf16 v[50:65], v[50:53], v[2:5], 0
	s_waitcnt lgkmcnt(6)
	v_mfma_f32_32x32x16_bf16 v[50:65], v[66:69], v[170:173], v[50:65]
	s_waitcnt lgkmcnt(5)
	v_mfma_f32_32x32x16_bf16 v[50:65], v[70:73], v[166:169], v[50:65]
	ds_read_b128 v[66:69], v0 offset:352
	ds_read_b128 v[70:73], v0 offset:320
	ds_read_b128 v[82:85], v0 offset:256
	ds_read_b128 v[106:109], v0 offset:288
	s_waitcnt lgkmcnt(8)
	v_mfma_f32_32x32x16_bf16 v[50:65], v[74:77], v[162:165], v[50:65]
	s_waitcnt lgkmcnt(7)
	v_mfma_f32_32x32x16_bf16 v[50:65], v[78:81], v[158:161], v[50:65]
	s_waitcnt lgkmcnt(6)
	v_mfma_f32_32x32x16_bf16 v[50:65], v[94:97], v[154:157], v[50:65]
	s_waitcnt lgkmcnt(5)
	v_mfma_f32_32x32x16_bf16 v[50:65], v[98:101], v[134:137], v[50:65]
	ds_read_b128 v[74:77], v0 offset:384
	ds_read_b128 v[78:81], v0 offset:416
	ds_read_b128 v[94:97], v0 offset:448
	ds_read_b128 v[98:101], v0 offset:480
	s_waitcnt lgkmcnt(8)
	v_mfma_f32_32x32x16_bf16 v[50:65], v[102:105], v[130:133], v[50:65]
	s_waitcnt lgkmcnt(5)
	v_mfma_f32_32x32x16_bf16 v[50:65], v[82:85], v[202:205], v[50:65]
	s_waitcnt lgkmcnt(4)
	v_mfma_f32_32x32x16_bf16 v[50:65], v[106:109], v[198:201], v[50:65]
	v_mfma_f32_32x32x16_bf16 v[50:65], v[70:73], v[194:197], v[50:65]
	v_mfma_f32_32x32x16_bf16 v[50:65], v[66:69], v[190:193], v[50:65]
	s_mov_b32 s27, 0x140000
	s_waitcnt vmcnt(3)
	ds_write_b128 v214, v[6:9] offset:16896
	s_waitcnt vmcnt(2)
	ds_write_b128 v214, v[10:13] offset:16912
	v_add_co_u32_e32 v6, vcc, s27, v14
	v_lshl_add_u64 v[10:11], v[14:15], 0, s[38:39]
	s_nop 0
	v_addc_co_u32_e32 v7, vcc, 0, v15, vcc
	s_waitcnt lgkmcnt(0)
	s_barrier
	global_load_dwordx4 v[6:9], v[6:7], off
	s_nop 0
	global_load_dwordx4 v[10:13], v[10:11], off offset:16
	v_mfma_f32_32x32x16_bf16 v[50:65], v[74:77], v[186:189], v[50:65]
	v_mfma_f32_32x32x16_bf16 v[50:65], v[78:81], v[182:185], v[50:65]
	v_mfma_f32_32x32x16_bf16 v[50:65], v[94:97], v[178:181], v[50:65]
	ds_read_b128 v[66:69], v0 offset:16896
	ds_read_b128 v[82:85], v0 offset:16928
	ds_read_b128 v[94:97], v0 offset:16960
	ds_read_b128 v[102:105], v0 offset:16992
	ds_read_b128 v[106:109], v0 offset:17024
	ds_read_b128 v[110:113], v0 offset:17056
	ds_read_b128 v[114:117], v0 offset:17088
	ds_read_b128 v[118:121], v0 offset:17120
	v_mfma_f32_32x32x16_bf16 v[50:65], v[98:101], v[174:177], v[50:65]
	s_waitcnt lgkmcnt(7)
	v_mfma_f32_32x32x16_bf16 v[66:81], v[66:69], v[2:5], 0
	s_waitcnt lgkmcnt(6)
	v_mfma_f32_32x32x16_bf16 v[66:81], v[82:85], v[170:173], v[66:81]
	s_waitcnt lgkmcnt(5)
	v_mfma_f32_32x32x16_bf16 v[66:81], v[94:97], v[166:169], v[66:81]
	ds_read_b128 v[82:85], v0 offset:17248
	ds_read_b128 v[94:97], v0 offset:17216
	ds_read_b128 v[98:101], v0 offset:17152
	ds_read_b128 v[122:125], v0 offset:17184
	s_waitcnt lgkmcnt(8)
	v_mfma_f32_32x32x16_bf16 v[66:81], v[102:105], v[162:165], v[66:81]
	s_waitcnt lgkmcnt(7)
	v_mfma_f32_32x32x16_bf16 v[66:81], v[106:109], v[158:161], v[66:81]
	s_waitcnt lgkmcnt(6)
	v_mfma_f32_32x32x16_bf16 v[66:81], v[110:113], v[154:157], v[66:81]
	s_waitcnt lgkmcnt(5)
	v_mfma_f32_32x32x16_bf16 v[66:81], v[114:117], v[134:137], v[66:81]
	ds_read_b128 v[102:105], v0 offset:17280
	ds_read_b128 v[106:109], v0 offset:17312
	ds_read_b128 v[110:113], v0 offset:17344
	ds_read_b128 v[114:117], v0 offset:17376
	s_waitcnt lgkmcnt(8)
	v_mfma_f32_32x32x16_bf16 v[66:81], v[118:121], v[130:133], v[66:81]
	s_waitcnt lgkmcnt(5)
	v_mfma_f32_32x32x16_bf16 v[66:81], v[98:101], v[202:205], v[66:81]
	s_waitcnt lgkmcnt(4)
	v_mfma_f32_32x32x16_bf16 v[66:81], v[122:125], v[198:201], v[66:81]
	v_mfma_f32_32x32x16_bf16 v[66:81], v[94:97], v[194:197], v[66:81]
	v_mfma_f32_32x32x16_bf16 v[66:81], v[82:85], v[190:193], v[66:81]
	v_add_co_u32_e32 v82, vcc, s58, v14
	s_waitcnt vmcnt(3)
	ds_write_b128 v214, v[86:89]
	s_waitcnt vmcnt(2)
	ds_write_b128 v214, v[90:93] offset:16
	v_addc_co_u32_e32 v83, vcc, 0, v15, vcc
	s_waitcnt lgkmcnt(0)
	s_barrier
; #define XLAS __attribute__((address_space(3)))
; __device__ __forceinline__ void unit(XLAS unsigned char* lds, const bf16_t* Qg, const bf16_t* Kg, const bf16_t* Vg, bf16_t* Og) {
;     ...
;     for (int c = 0; c < 8; ++c) {
;         XLAS unsigned char* buf = lds + (c & 1) * CHB;
;         *(XLAS u32x4*)(buf + wofs) = g[c & 1][0]; *(XLAS u32x4*)(buf + wofs + 16) = g[c & 1][1];
;         __syncthreads();
;         { g[c & 1][0] = *(const u32x4*)(XAT_SRC(c + 2)); g[c & 1][1] = *(const u32x4*)(XAT_SRC(c + 2) + 8); }
;         f32x16 a = {};
;         bf16x8 kfa[4], kfb[4];
; #pragma unroll
;         for (int j = 0; j < 4; ++j) kfa[j] = *(const XLAS bf16x8*)(buf + kro + j * 32);
; #pragma unroll
;         for (int gq = 0; gq < 4; gq += 2) {
; #pragma unroll
;             for (int j = 0; j < 4; ++j) kfb[j] = *(const XLAS bf16x8*)(buf + kro + (4 * gq + 4 + j) * 32);
;             __builtin_amdgcn_sched_barrier(0);
; #pragma unroll
;             for (int j = 0; j < 4; ++j) a = __builtin_amdgcn_mfma_f32_32x32x16_bf16(kfa[j], qf[4 * gq + j], a, 0, 0, 0);
;             if (gq < 2) {
; #pragma unroll
;                 for (int j = 0; j < 4; ++j) kfa[j] = *(const XLAS bf16x8*)(buf + kro + (4 * gq + 8 + j) * 32); }
;             __builtin_amdgcn_sched_barrier(0);
; #pragma unroll
;             for (int j = 0; j < 4; ++j) a = __builtin_amdgcn_mfma_f32_32x32x16_bf16(kfb[j], qf[4 * gq + 4 + j], a, 0, 0, 0);
;         }
;         S[c] = a;
;     }
	v_lshl_add_u64 v[16:17], v[14:15], 0, s[56:57]
	global_load_dwordx4 v[118:121], v[82:83], off
	global_load_dwordx4 v[122:125], v[16:17], off offset:16
	v_mfma_f32_32x32x16_bf16 v[66:81], v[102:105], v[186:189], v[66:81]
	v_mfma_f32_32x32x16_bf16 v[66:81], v[106:109], v[182:185], v[66:81]
	v_mfma_f32_32x32x16_bf16 v[66:81], v[110:113], v[178:181], v[66:81]
	ds_read_b128 v[82:85], v0
	ds_read_b128 v[98:101], v0 offset:32
	ds_read_b128 v[102:105], v0 offset:64
	ds_read_b128 v[106:109], v0 offset:96
	ds_read_b128 v[110:113], v0 offset:128
	ds_read_b128 v[126:129], v0 offset:160
	ds_read_b128 v[138:141], v0 offset:192
	ds_read_b128 v[142:145], v0 offset:224
	v_mfma_f32_32x32x16_bf16 v[66:81], v[114:117], v[174:177], v[66:81]
	s_waitcnt lgkmcnt(7)
	v_mfma_f32_32x32x16_bf16 v[82:97], v[82:85], v[2:5], 0
	s_waitcnt lgkmcnt(6)
	v_mfma_f32_32x32x16_bf16 v[82:97], v[98:101], v[170:173], v[82:97]
	s_waitcnt lgkmcnt(5)
	v_mfma_f32_32x32x16_bf16 v[82:97], v[102:105], v[166:169], v[82:97]
	ds_read_b128 v[98:101], v0 offset:352
	ds_read_b128 v[102:105], v0 offset:320
	ds_read_b128 v[114:117], v0 offset:256
	ds_read_b128 v[146:149], v0 offset:288
	s_waitcnt lgkmcnt(8)
	v_mfma_f32_32x32x16_bf16 v[82:97], v[106:109], v[162:165], v[82:97]
	s_waitcnt lgkmcnt(7)
	v_mfma_f32_32x32x16_bf16 v[82:97], v[110:113], v[158:161], v[82:97]
	s_waitcnt lgkmcnt(6)
	v_mfma_f32_32x32x16_bf16 v[82:97], v[126:129], v[154:157], v[82:97]
	s_waitcnt lgkmcnt(5)
	v_mfma_f32_32x32x16_bf16 v[82:97], v[138:141], v[134:137], v[82:97]
	ds_read_b128 v[106:109], v0 offset:384
	ds_read_b128 v[110:113], v0 offset:416
	ds_read_b128 v[126:129], v0 offset:448
	ds_read_b128 v[138:141], v0 offset:480
	s_waitcnt lgkmcnt(8)
	v_mfma_f32_32x32x16_bf16 v[82:97], v[142:145], v[130:133], v[82:97]
	s_waitcnt lgkmcnt(5)
	v_mfma_f32_32x32x16_bf16 v[82:97], v[114:117], v[202:205], v[82:97]
	s_waitcnt lgkmcnt(4)
	v_mfma_f32_32x32x16_bf16 v[82:97], v[146:149], v[198:201], v[82:97]
	v_mfma_f32_32x32x16_bf16 v[82:97], v[102:105], v[194:197], v[82:97]
	v_mfma_f32_32x32x16_bf16 v[82:97], v[98:101], v[190:193], v[82:97]
	s_waitcnt vmcnt(3)
	ds_write_b128 v214, v[6:9] offset:16896
	s_waitcnt vmcnt(2)
	ds_write_b128 v214, v[10:13] offset:16912
	v_add_co_u32_e32 v6, vcc, s59, v14
	v_lshl_add_u64 v[10:11], v[14:15], 0, s[60:61]
	s_nop 0
	v_addc_co_u32_e32 v7, vcc, 0, v15, vcc
	s_waitcnt lgkmcnt(0)
	s_barrier
	global_load_dwordx4 v[6:9], v[6:7], off
	s_nop 0
	global_load_dwordx4 v[10:13], v[10:11], off offset:16
	v_mfma_f32_32x32x16_bf16 v[82:97], v[106:109], v[186:189], v[82:97]
	v_mfma_f32_32x32x16_bf16 v[82:97], v[110:113], v[182:185], v[82:97]
	v_mfma_f32_32x32x16_bf16 v[82:97], v[126:129], v[178:181], v[82:97]
	ds_read_b128 v[14:17], v0 offset:16896
	ds_read_b128 v[114:117], v0 offset:16928
	ds_read_b128 v[126:129], v0 offset:16960
	ds_read_b128 v[142:145], v0 offset:16992
	ds_read_b128 v[146:149], v0 offset:17024
	ds_read_b128 v[150:153], v0 offset:17056
	ds_read_b128 v[220:223], v0 offset:17088
	ds_read_b128 v[224:227], v0 offset:17120
	v_mfma_f32_32x32x16_bf16 v[82:97], v[138:141], v[174:177], v[82:97]
	s_waitcnt lgkmcnt(7)
	v_mfma_f32_32x32x16_bf16 v[98:113], v[14:17], v[2:5], 0
	s_waitcnt lgkmcnt(6)
	v_mfma_f32_32x32x16_bf16 v[98:113], v[114:117], v[170:173], v[98:113]
	s_waitcnt lgkmcnt(5)
	v_mfma_f32_32x32x16_bf16 v[98:113], v[126:129], v[166:169], v[98:113]
	ds_read_b128 v[14:17], v0 offset:17248
	ds_read_b128 v[114:117], v0 offset:17216
	ds_read_b128 v[126:129], v0 offset:17152
	ds_read_b128 v[138:141], v0 offset:17184
	s_waitcnt lgkmcnt(8)
	v_mfma_f32_32x32x16_bf16 v[98:113], v[142:145], v[162:165], v[98:113]
	s_waitcnt lgkmcnt(7)
	v_mfma_f32_32x32x16_bf16 v[98:113], v[146:149], v[158:161], v[98:113]
	s_waitcnt lgkmcnt(6)
	v_mfma_f32_32x32x16_bf16 v[98:113], v[150:153], v[154:157], v[98:113]
	s_waitcnt lgkmcnt(5)
	v_mfma_f32_32x32x16_bf16 v[98:113], v[220:223], v[134:137], v[98:113]
	ds_read_b128 v[142:145], v0 offset:17280
	ds_read_b128 v[146:149], v0 offset:17312
	ds_read_b128 v[220:223], v0 offset:17344
	ds_read_b128 v[228:231], v0 offset:17376
	s_waitcnt lgkmcnt(8)
	v_mfma_f32_32x32x16_bf16 v[98:113], v[224:227], v[130:133], v[98:113]
	s_waitcnt lgkmcnt(5)
	v_mfma_f32_32x32x16_bf16 v[98:113], v[126:129], v[202:205], v[98:113]
	s_waitcnt lgkmcnt(4)
	v_mfma_f32_32x32x16_bf16 v[98:113], v[138:141], v[198:201], v[98:113]
	v_mfma_f32_32x32x16_bf16 v[98:113], v[114:117], v[194:197], v[98:113]
	v_mfma_f32_32x32x16_bf16 v[98:113], v[14:17], v[190:193], v[98:113]
	s_waitcnt lgkmcnt(3)
	v_mfma_f32_32x32x16_bf16 v[98:113], v[142:145], v[186:189], v[98:113]
	s_waitcnt vmcnt(3)
	ds_write_b128 v214, v[118:121]
	s_waitcnt vmcnt(2)
	ds_write_b128 v214, v[122:125] offset:16
	s_waitcnt lgkmcnt(0)
	s_barrier
; #define XLAS __attribute__((address_space(3)))
; __device__ __forceinline__ void unit(XLAS unsigned char* lds, const bf16_t* Qg, const bf16_t* Kg, const bf16_t* Vg, bf16_t* Og) {
;     ...
;     for (int c = 0; c < 8; ++c) {
;         XLAS unsigned char* buf = lds + (c & 1) * CHB;
;         *(XLAS u32x4*)(buf + wofs) = g[c & 1][0]; *(XLAS u32x4*)(buf + wofs + 16) = g[c & 1][1];
;         __syncthreads();
;         { g[c & 1][0] = *(const u32x4*)(XAT_SRC(c + 2)); g[c & 1][1] = *(const u32x4*)(XAT_SRC(c + 2) + 8); }
;         f32x16 a = {};
;         bf16x8 kfa[4], kfb[4];
; #pragma unroll
;         for (int j = 0; j < 4; ++j) kfa[j] = *(const XLAS bf16x8*)(buf + kro + j * 32);
; #pragma unroll
;         for (int gq = 0; gq < 4; gq += 2) {
; #pragma unroll
;             for (int j = 0; j < 4; ++j) kfb[j] = *(const XLAS bf16x8*)(buf + kro + (4 * gq + 4 + j) * 32);
;             __builtin_amdgcn_sched_barrier(0);
; #pragma unroll
;             for (int j = 0; j < 4; ++j) a = __builtin_amdgcn_mfma_f32_32x32x16_bf16(kfa[j], qf[4 * gq + j], a, 0, 0, 0);
;             if (gq < 2) {
; #pragma unroll
;                 for (int j = 0; j < 4; ++j) kfa[j] = *(const XLAS bf16x8*)(buf + kro + (4 * gq + 8 + j) * 32); }
;             __builtin_amdgcn_sched_barrier(0);
; #pragma unroll
;             for (int j = 0; j < 4; ++j) a = __builtin_amdgcn_mfma_f32_32x32x16_bf16(kfb[j], qf[4 * gq + 4 + j], a, 0, 0, 0);
;         }
;         S[c] = a;
;     }
;     float mx = S[0][0];
; #pragma unroll
;     for (int c = 0; c < 8; ++c)
; #pragma unroll
;         for (int r = 0; r < 16; ++r) mx = __builtin_fmaxf(mx, S[c][r]);
;     mx = __builtin_fmaxf(mx, __shfl_xor(mx, 32));
	v_mfma_f32_32x32x16_bf16 v[98:113], v[146:149], v[182:185], v[98:113]
	global_load_dwordx4 v[146:149], v[212:213], off offset:16
	global_load_dwordx4 v[150:153], v[212:213], off
	v_mfma_f32_32x32x16_bf16 v[98:113], v[220:223], v[178:181], v[98:113]
	ds_read_b128 v[14:17], v0
	ds_read_b128 v[138:141], v0 offset:32
	ds_read_b128 v[142:145], v0 offset:64
	ds_read_b128 v[220:223], v0 offset:96
	ds_read_b128 v[224:227], v0 offset:128
	ds_read_b128 v[232:235], v0 offset:160
	ds_read_b128 v[236:239], v0 offset:192
	ds_read_b128 v[240:243], v0 offset:224
	v_mfma_f32_32x32x16_bf16 v[98:113], v[228:231], v[174:177], v[98:113]
	s_waitcnt lgkmcnt(7)
	v_mfma_f32_32x32x16_bf16 v[114:129], v[14:17], v[2:5], 0
	s_waitcnt lgkmcnt(6)
	v_mfma_f32_32x32x16_bf16 v[114:129], v[138:141], v[170:173], v[114:129]
	s_waitcnt lgkmcnt(5)
	v_mfma_f32_32x32x16_bf16 v[114:129], v[142:145], v[166:169], v[114:129]
	ds_read_b128 v[14:17], v0 offset:352
	ds_read_b128 v[138:141], v0 offset:320
	ds_read_b128 v[142:145], v0 offset:256
	ds_read_b128 v[228:231], v0 offset:288
	s_waitcnt lgkmcnt(8)
	v_mfma_f32_32x32x16_bf16 v[114:129], v[220:223], v[162:165], v[114:129]
	s_waitcnt lgkmcnt(7)
	v_mfma_f32_32x32x16_bf16 v[114:129], v[224:227], v[158:161], v[114:129]
	s_waitcnt lgkmcnt(6)
	v_mfma_f32_32x32x16_bf16 v[114:129], v[232:235], v[154:157], v[114:129]
	s_waitcnt lgkmcnt(5)
	v_mfma_f32_32x32x16_bf16 v[114:129], v[236:239], v[134:137], v[114:129]
	ds_read_b128 v[220:223], v0 offset:384
	ds_read_b128 v[224:227], v0 offset:416
	ds_read_b128 v[232:235], v0 offset:448
	ds_read_b128 v[236:239], v0 offset:480
	s_waitcnt lgkmcnt(8)
	v_mfma_f32_32x32x16_bf16 v[114:129], v[240:243], v[130:133], v[114:129]
	s_waitcnt lgkmcnt(5)
	v_mfma_f32_32x32x16_bf16 v[114:129], v[142:145], v[202:205], v[114:129]
	s_waitcnt lgkmcnt(4)
	v_mfma_f32_32x32x16_bf16 v[114:129], v[228:231], v[198:201], v[114:129]
	v_mfma_f32_32x32x16_bf16 v[114:129], v[138:141], v[194:197], v[114:129]
	v_mfma_f32_32x32x16_bf16 v[114:129], v[14:17], v[190:193], v[114:129]
	s_waitcnt vmcnt(3)
	ds_write_b128 v214, v[6:9] offset:16896
	s_waitcnt vmcnt(2)
	ds_write_b128 v214, v[10:13] offset:16912
	v_add_co_u32_e32 v8, vcc, s45, v212
	s_waitcnt lgkmcnt(0)
	s_nop 0
	v_addc_co_u32_e32 v9, vcc, 0, v213, vcc
	s_barrier
	v_lshl_add_u64 v[6:7], v[212:213], 0, s[22:23]
	global_load_dwordx4 v[142:145], v[8:9], off
	global_load_dwordx4 v[138:141], v[6:7], off offset:16
	v_mfma_f32_32x32x16_bf16 v[114:129], v[220:223], v[186:189], v[114:129]
	v_mfma_f32_32x32x16_bf16 v[114:129], v[224:227], v[182:185], v[114:129]
	v_mfma_f32_32x32x16_bf16 v[114:129], v[232:235], v[178:181], v[114:129]
	ds_read_b128 v[6:9], v0 offset:16896
	ds_read_b128 v[220:223], v0 offset:16928
	ds_read_b128 v[224:227], v0 offset:16960
	ds_read_b128 v[228:231], v0 offset:16992
	ds_read_b128 v[232:235], v0 offset:17024
	ds_read_b128 v[240:243], v0 offset:17056
	ds_read_b128 v[250:253], v0 offset:17088
	ds_read_b128 v[208:211], v0 offset:17120
	v_mfma_f32_32x32x16_bf16 v[114:129], v[236:239], v[174:177], v[114:129]
	s_waitcnt lgkmcnt(7)
	v_mfma_f32_32x32x16_bf16 v[2:17], v[6:9], v[2:5], 0
	s_waitcnt lgkmcnt(6)
	v_mfma_f32_32x32x16_bf16 v[2:17], v[220:223], v[170:173], v[2:17]
	s_waitcnt lgkmcnt(5)
	v_mfma_f32_32x32x16_bf16 v[2:17], v[224:227], v[166:169], v[2:17]
	ds_read_b128 v[166:169], v0 offset:17248
	ds_read_b128 v[170:173], v0 offset:17216
	ds_read_b128 v[220:223], v0 offset:17152
	ds_read_b128 v[224:227], v0 offset:17184
	s_waitcnt lgkmcnt(8)
	v_mfma_f32_32x32x16_bf16 v[2:17], v[228:231], v[162:165], v[2:17]
	s_waitcnt lgkmcnt(7)
	v_mfma_f32_32x32x16_bf16 v[2:17], v[232:235], v[158:161], v[2:17]
	s_waitcnt lgkmcnt(6)
	v_mfma_f32_32x32x16_bf16 v[2:17], v[240:243], v[154:157], v[2:17]
	s_waitcnt lgkmcnt(5)
	v_mfma_f32_32x32x16_bf16 v[2:17], v[250:253], v[134:137], v[2:17]
	ds_read_b128 v[134:137], v0 offset:17280
	ds_read_b128 v[154:157], v0 offset:17312
	ds_read_b128 v[158:161], v0 offset:17344
	ds_read_b128 v[162:165], v0 offset:17376
	s_waitcnt lgkmcnt(8)
	v_mfma_f32_32x32x16_bf16 v[2:17], v[208:211], v[130:133], v[2:17]
	s_waitcnt lgkmcnt(5)
	v_mfma_f32_32x32x16_bf16 v[2:17], v[220:223], v[202:205], v[2:17]
	s_waitcnt lgkmcnt(4)
	v_mfma_f32_32x32x16_bf16 v[2:17], v[224:227], v[198:201], v[2:17]
	v_mfma_f32_32x32x16_bf16 v[2:17], v[170:173], v[194:197], v[2:17]
	v_mfma_f32_32x32x16_bf16 v[2:17], v[166:169], v[190:193], v[2:17]
	v_max_f32_e32 v0, v19, v19
	v_max_f32_e32 v130, v18, v18
	v_max_f32_e32 v0, v130, v0
	v_max3_f32 v0, v0, v20, v21
	v_max3_f32 v0, v0, v22, v23
	v_max3_f32 v0, v0, v24, v25
	v_max3_f32 v0, v0, v26, v27
	v_max3_f32 v0, v0, v28, v29
	v_max3_f32 v0, v0, v30, v31
	v_max3_f32 v0, v0, v32, v33
	v_max3_f32 v0, v0, v34, v35
	v_max3_f32 v0, v0, v36, v37
	v_max3_f32 v0, v0, v38, v39
	v_max3_f32 v0, v0, v40, v41
	v_max3_f32 v0, v0, v42, v43
	v_max3_f32 v0, v0, v44, v45
	v_max3_f32 v0, v0, v46, v47
	v_max3_f32 v0, v0, v48, v49
	v_max3_f32 v0, v0, v50, v51
	v_max3_f32 v0, v0, v52, v53
	v_max3_f32 v0, v0, v54, v55
	v_max3_f32 v0, v0, v56, v57
	v_max3_f32 v0, v0, v58, v59
	v_max3_f32 v0, v0, v60, v61
	v_max3_f32 v0, v0, v62, v63
	v_max3_f32 v0, v0, v64, v65
	s_waitcnt lgkmcnt(3)
	v_mfma_f32_32x32x16_bf16 v[2:17], v[134:137], v[186:189], v[2:17]
	v_max3_f32 v0, v0, v66, v67
	v_max3_f32 v0, v0, v68, v69
	v_max3_f32 v0, v0, v70, v71
	v_max3_f32 v0, v0, v72, v73
	v_max3_f32 v0, v0, v74, v75
	v_max3_f32 v0, v0, v76, v77
	v_max3_f32 v0, v0, v78, v79
	v_max3_f32 v0, v0, v80, v81
	s_waitcnt lgkmcnt(2)
	v_mfma_f32_32x32x16_bf16 v[2:17], v[154:157], v[182:185], v[2:17]
	v_max3_f32 v0, v0, v82, v83
	v_max3_f32 v0, v0, v84, v85
	v_max3_f32 v0, v0, v86, v87
	v_max3_f32 v0, v0, v88, v89
	v_max3_f32 v0, v0, v90, v91
	v_max3_f32 v0, v0, v92, v93
	v_max3_f32 v0, v0, v94, v95
	v_max3_f32 v0, v0, v96, v97
	s_waitcnt lgkmcnt(1)
	v_mfma_f32_32x32x16_bf16 v[2:17], v[158:161], v[178:181], v[2:17]
	v_max3_f32 v0, v0, v98, v99
	v_max3_f32 v0, v0, v100, v101
	v_max3_f32 v0, v0, v102, v103
	v_max3_f32 v0, v0, v104, v105
	v_max3_f32 v0, v0, v106, v107
	v_max3_f32 v0, v0, v108, v109
	v_max3_f32 v0, v0, v110, v111
	v_max3_f32 v0, v0, v112, v113
	s_waitcnt lgkmcnt(0)
	v_mfma_f32_32x32x16_bf16 v[2:17], v[162:165], v[174:177], v[2:17]
	v_max3_f32 v0, v0, v114, v115
	v_max3_f32 v0, v0, v116, v117
	v_max3_f32 v0, v0, v118, v119
	v_max3_f32 v0, v0, v120, v121
	v_max3_f32 v0, v0, v122, v123
	v_max3_f32 v0, v0, v124, v125
	v_max3_f32 v0, v0, v126, v127
	v_max3_f32 v0, v0, v128, v129
	s_nop 3
	v_max3_f32 v0, v0, v2, v3
	v_max3_f32 v0, v0, v4, v5
	v_max3_f32 v0, v0, v6, v7
	v_max3_f32 v0, v0, v8, v9
	v_max3_f32 v0, v0, v10, v11
	v_max3_f32 v0, v0, v12, v13
	v_max3_f32 v0, v0, v14, v15
	v_and_b32_e32 v131, 64, v246
	v_max3_f32 v130, v0, v16, v17
	v_xor_b32_e32 v0, 32, v246
	v_add_u32_e32 v131, 64, v131
	v_cmp_lt_i32_e32 vcc, v0, v131
	s_waitcnt vmcnt(2)
	ds_write_b128 v214, v[150:153]
	ds_write_b128 v214, v[146:149] offset:16
	v_cndmask_b32_e32 v0, v246, v0, vcc
	v_lshlrev_b32_e32 v0, 2, v0
	ds_bpermute_b32 v131, v0, v130
	s_waitcnt lgkmcnt(0)
	s_barrier
; __device__ __forceinline__ unsigned cvtpk(float lo, float hi) { f32x2_t v = {lo, hi}; bf16x2_t b = __builtin_convertvector(v, bf16x2_t); return __builtin_bit_cast(unsigned, b); }
; __device__ __forceinline__ void unit(XLAS unsigned char* lds, const bf16_t* Qg, const bf16_t* Kg, const bf16_t* Vg, bf16_t* Og) {
;     ...
; #pragma unroll
;     for (int c = 0; c < 8; ++c) {
;         f32x16 p;
; #pragma unroll
;         for (int r = 0; r < 16; ++r) { p[r] = __builtin_amdgcn_exp2f(S[c][r] - mx); l += p[r]; }
; #pragma unroll
;         for (int s = 0; s < 2; ++s) { pw[c][s].x = cvtpk(p[8 * s + 0], p[8 * s + 1]); pw[c][s].y = cvtpk(p[8 * s + 2], p[8 * s + 3]); pw[c][s].z = cvtpk(p[8 * s + 4], p[8 * s + 5]); pw[c][s].w = cvtpk(p[8 * s + 6], p[8 * s + 7]); }
;     }
	s_add_u32 s48, s48, s0
	v_max_f32_e32 v131, v131, v131
	v_max_f32_e32 v154, v130, v131
	v_sub_f32_e32 v18, v18, v154
	v_sub_f32_e32 v19, v19, v154
	v_exp_f32_e32 v18, v18
	v_exp_f32_e32 v19, v19
	v_sub_f32_e32 v20, v20, v154
	v_exp_f32_e32 v20, v20
	v_sub_f32_e32 v21, v21, v154
	v_exp_f32_e32 v21, v21
	v_sub_f32_e32 v22, v22, v154
	v_exp_f32_e32 v22, v22
	v_sub_f32_e32 v23, v23, v154
	v_cvt_pk_bf16_f32 v130, v18, v19
	v_add_f32_e32 v18, 0, v18
	v_exp_f32_e32 v23, v23
	v_sub_f32_e32 v24, v24, v154
	v_add_f32_e32 v18, v19, v18
	v_exp_f32_e32 v24, v24
	v_sub_f32_e32 v25, v25, v154
	v_add_f32_e32 v18, v20, v18
	v_exp_f32_e32 v25, v25
	v_sub_f32_e32 v26, v26, v154
	v_add_f32_e32 v18, v21, v18
	v_exp_f32_e32 v26, v26
	v_sub_f32_e32 v27, v27, v154
	v_add_f32_e32 v18, v22, v18
	v_exp_f32_e32 v27, v27
	v_sub_f32_e32 v28, v28, v154
	v_add_f32_e32 v18, v23, v18
	v_exp_f32_e32 v28, v28
	v_sub_f32_e32 v29, v29, v154
	v_add_f32_e32 v18, v24, v18
	v_exp_f32_e32 v29, v29
	v_sub_f32_e32 v30, v30, v154
	v_add_f32_e32 v18, v25, v18
	v_exp_f32_e32 v30, v30
	v_sub_f32_e32 v31, v31, v154
	v_add_f32_e32 v18, v26, v18
	v_exp_f32_e32 v31, v31
	v_sub_f32_e32 v32, v32, v154
	v_add_f32_e32 v18, v27, v18
	v_exp_f32_e32 v32, v32
	v_sub_f32_e32 v33, v33, v154
	v_add_f32_e32 v18, v28, v18
	v_exp_f32_e32 v33, v33
	v_add_f32_e32 v18, v29, v18
	v_sub_f32_e32 v19, v34, v154
	v_cvt_pk_bf16_f32 v131, v20, v21
	v_add_f32_e32 v18, v30, v18
	v_exp_f32_e32 v19, v19
	v_sub_f32_e32 v20, v35, v154
	v_add_f32_e32 v18, v31, v18
	v_exp_f32_e32 v20, v20
	v_sub_f32_e32 v21, v36, v154
	v_cvt_pk_bf16_f32 v132, v22, v23
	v_add_f32_e32 v18, v32, v18
	v_exp_f32_e32 v21, v21
	v_sub_f32_e32 v22, v37, v154
	v_add_f32_e32 v18, v33, v18
	v_exp_f32_e32 v22, v22
	v_sub_f32_e32 v23, v38, v154
	v_cvt_pk_bf16_f32 v133, v24, v25
	v_exp_f32_e32 v23, v23
	v_sub_f32_e32 v24, v39, v154
	v_add_f32_e32 v18, v19, v18
	v_exp_f32_e32 v24, v24
	v_sub_f32_e32 v25, v40, v154
	v_add_f32_e32 v18, v20, v18
	v_cvt_pk_bf16_f32 v134, v26, v27
	v_exp_f32_e32 v25, v25
	v_sub_f32_e32 v26, v41, v154
	v_add_f32_e32 v18, v21, v18
	v_exp_f32_e32 v26, v26
	v_sub_f32_e32 v27, v42, v154
	v_add_f32_e32 v18, v22, v18
	v_cvt_pk_bf16_f32 v135, v28, v29
	v_exp_f32_e32 v27, v27
	v_sub_f32_e32 v28, v43, v154
	v_add_f32_e32 v18, v23, v18
	v_exp_f32_e32 v28, v28
	v_sub_f32_e32 v29, v44, v154
	v_add_f32_e32 v18, v24, v18
	v_cvt_pk_bf16_f32 v136, v30, v31
	v_exp_f32_e32 v29, v29
	v_sub_f32_e32 v30, v45, v154
	v_add_f32_e32 v18, v25, v18
	v_exp_f32_e32 v30, v30
	v_sub_f32_e32 v31, v46, v154
	v_add_f32_e32 v18, v26, v18
	v_cvt_pk_bf16_f32 v137, v32, v33
	v_exp_f32_e32 v31, v31
	v_sub_f32_e32 v32, v47, v154
	v_add_f32_e32 v18, v27, v18
	v_exp_f32_e32 v32, v32
	v_sub_f32_e32 v33, v48, v154
	v_add_f32_e32 v18, v28, v18
	v_exp_f32_e32 v33, v33
	v_sub_f32_e32 v34, v49, v154
	v_add_f32_e32 v18, v29, v18
	v_exp_f32_e32 v42, v34
	v_cvt_pk_bf16_f32 v34, v19, v20
	v_add_f32_e32 v18, v30, v18
	v_sub_f32_e32 v19, v50, v154
	v_add_f32_e32 v18, v31, v18
	v_exp_f32_e32 v19, v19
	v_sub_f32_e32 v20, v51, v154
	v_cvt_pk_bf16_f32 v35, v21, v22
	v_add_f32_e32 v18, v32, v18
	v_exp_f32_e32 v20, v20
	v_sub_f32_e32 v21, v52, v154
	v_add_f32_e32 v18, v33, v18
	v_exp_f32_e32 v21, v21
	v_sub_f32_e32 v22, v53, v154
	v_cvt_pk_bf16_f32 v36, v23, v24
	v_add_f32_e32 v18, v42, v18
	v_exp_f32_e32 v22, v22
	v_sub_f32_e32 v23, v54, v154
	v_exp_f32_e32 v23, v23
	v_sub_f32_e32 v24, v55, v154
	v_add_f32_e32 v18, v19, v18
	v_cvt_pk_bf16_f32 v37, v25, v26
	v_exp_f32_e32 v24, v24
	v_sub_f32_e32 v25, v56, v154
	v_add_f32_e32 v18, v20, v18
	v_exp_f32_e32 v25, v25
	v_sub_f32_e32 v26, v57, v154
	v_add_f32_e32 v18, v21, v18
	v_cvt_pk_bf16_f32 v38, v27, v28
	v_exp_f32_e32 v26, v26
	v_sub_f32_e32 v27, v58, v154
	v_add_f32_e32 v18, v22, v18
	v_exp_f32_e32 v27, v27
	v_sub_f32_e32 v28, v59, v154
	v_add_f32_e32 v18, v23, v18
	v_cvt_pk_bf16_f32 v39, v29, v30
	v_exp_f32_e32 v28, v28
	v_sub_f32_e32 v29, v60, v154
	v_add_f32_e32 v18, v24, v18
	v_exp_f32_e32 v29, v29
	v_sub_f32_e32 v30, v61, v154
	v_add_f32_e32 v18, v25, v18
	v_cvt_pk_bf16_f32 v40, v31, v32
	v_exp_f32_e32 v30, v30
	v_sub_f32_e32 v31, v62, v154
	v_add_f32_e32 v18, v26, v18
	v_exp_f32_e32 v31, v31
	v_sub_f32_e32 v32, v63, v154
	v_add_f32_e32 v18, v27, v18
	v_cvt_pk_bf16_f32 v41, v33, v42
	v_exp_f32_e32 v32, v32
	v_sub_f32_e32 v33, v64, v154
	v_add_f32_e32 v18, v28, v18
	v_exp_f32_e32 v33, v33
	v_sub_f32_e32 v42, v65, v154
	v_add_f32_e32 v18, v29, v18
	v_exp_f32_e32 v50, v42
	v_cvt_pk_bf16_f32 v42, v19, v20
	v_add_f32_e32 v18, v30, v18
	v_sub_f32_e32 v19, v66, v154
	v_add_f32_e32 v18, v31, v18
	v_exp_f32_e32 v19, v19
	v_sub_f32_e32 v20, v67, v154
	v_cvt_pk_bf16_f32 v43, v21, v22
	v_add_f32_e32 v18, v32, v18
	v_exp_f32_e32 v20, v20
	v_sub_f32_e32 v21, v68, v154
	v_add_f32_e32 v18, v33, v18
	v_exp_f32_e32 v21, v21
	v_sub_f32_e32 v22, v69, v154
	v_cvt_pk_bf16_f32 v44, v23, v24
	v_add_f32_e32 v18, v50, v18
	v_exp_f32_e32 v22, v22
	v_sub_f32_e32 v23, v70, v154
	v_exp_f32_e32 v23, v23
	v_sub_f32_e32 v24, v71, v154
	v_add_f32_e32 v18, v19, v18
	v_cvt_pk_bf16_f32 v45, v25, v26
	v_exp_f32_e32 v24, v24
	v_sub_f32_e32 v25, v72, v154
	v_add_f32_e32 v18, v20, v18
	v_exp_f32_e32 v25, v25
	v_sub_f32_e32 v26, v73, v154
	v_add_f32_e32 v18, v21, v18
	v_cvt_pk_bf16_f32 v46, v27, v28
	v_exp_f32_e32 v26, v26
	v_sub_f32_e32 v27, v74, v154
	v_add_f32_e32 v18, v22, v18
	v_exp_f32_e32 v27, v27
	v_sub_f32_e32 v28, v75, v154
	v_add_f32_e32 v18, v23, v18
	v_cvt_pk_bf16_f32 v47, v29, v30
	v_exp_f32_e32 v28, v28
	v_sub_f32_e32 v29, v76, v154
	v_add_f32_e32 v18, v24, v18
	v_exp_f32_e32 v29, v29
	v_sub_f32_e32 v30, v77, v154
	v_add_f32_e32 v18, v25, v18
; #define XLAS __attribute__((address_space(3)))
; __device__ __forceinline__ unsigned cvtpk(float lo, float hi) { f32x2_t v = {lo, hi}; bf16x2_t b = __builtin_convertvector(v, bf16x2_t); return __builtin_bit_cast(unsigned, b); }
; __device__ __forceinline__ void unit(XLAS unsigned char* lds, const bf16_t* Qg, const bf16_t* Kg, const bf16_t* Vg, bf16_t* Og) {
;     ...
; #pragma unroll
;     for (int c = 0; c < 8; ++c) {
;         f32x16 p;
; #pragma unroll
;         for (int r = 0; r < 16; ++r) { p[r] = __builtin_amdgcn_exp2f(S[c][r] - mx); l += p[r]; }
; #pragma unroll
;         for (int s = 0; s < 2; ++s) { pw[c][s].x = cvtpk(p[8 * s + 0], p[8 * s + 1]); pw[c][s].y = cvtpk(p[8 * s + 2], p[8 * s + 3]); pw[c][s].z = cvtpk(p[8 * s + 4], p[8 * s + 5]); pw[c][s].w = cvtpk(p[8 * s + 6], p[8 * s + 7]); }
;     }
;     l += __shfl_xor(l, 32);
;     const float rl = 1.0f / l;
;     bf16_t* obase = Og + (size_t)(wid * 32 + (lane >> 3)) * 1024 + (lane & 7) * 8;
; #pragma unroll
;     for (int db = 0; db < 8; ++db) {
;         XLAS unsigned char* buf = lds + (db & 1) * CHB;
;         *(XLAS u32x4*)(buf + wofs) = g[db & 1][0]; *(XLAS u32x4*)(buf + wofs + 16) = g[db & 1][1];
;         __syncthreads();
;         if (db < 6) { g[db & 1][0] = *(const u32x4*)(XAT_SRC(db + 10)); g[db & 1][1] = *(const u32x4*)(XAT_SRC(db + 10) + 8); }
;         f32x16 o = {};
; #pragma unroll
;         for (int kb = 0; kb < 8; ++kb)
; #pragma unroll
;             for (int s = 0; s < 2; ++s) { const bf16x8 vf = *(const XLAS bf16x8*)(buf + vro + kb * 64 + s * 32); o = __builtin_amdgcn_mfma_f32_32x32x16_bf16(vf, __builtin_bit_cast(bf16x8, pw[kb][s]), o, 0, 0, 0); }
	v_cvt_pk_bf16_f32 v48, v31, v32
	v_exp_f32_e32 v30, v30
	v_sub_f32_e32 v31, v78, v154
	v_add_f32_e32 v18, v26, v18
	v_exp_f32_e32 v31, v31
	v_sub_f32_e32 v32, v79, v154
	v_add_f32_e32 v18, v27, v18
	v_cvt_pk_bf16_f32 v49, v33, v50
	v_exp_f32_e32 v32, v32
	v_sub_f32_e32 v33, v80, v154
	v_add_f32_e32 v18, v28, v18
	v_exp_f32_e32 v33, v33
	v_sub_f32_e32 v50, v81, v154
	v_add_f32_e32 v18, v29, v18
	v_exp_f32_e32 v58, v50
	v_cvt_pk_bf16_f32 v50, v19, v20
	v_add_f32_e32 v18, v30, v18
	v_sub_f32_e32 v19, v82, v154
	v_add_f32_e32 v18, v31, v18
	v_exp_f32_e32 v19, v19
	v_sub_f32_e32 v20, v83, v154
	v_cvt_pk_bf16_f32 v51, v21, v22
	v_add_f32_e32 v18, v32, v18
	v_exp_f32_e32 v20, v20
	v_sub_f32_e32 v21, v84, v154
	v_add_f32_e32 v18, v33, v18
	v_exp_f32_e32 v21, v21
	v_sub_f32_e32 v22, v85, v154
	v_cvt_pk_bf16_f32 v52, v23, v24
	v_add_f32_e32 v18, v58, v18
	v_exp_f32_e32 v22, v22
	v_sub_f32_e32 v23, v86, v154
	v_exp_f32_e32 v23, v23
	v_sub_f32_e32 v24, v87, v154
	v_add_f32_e32 v18, v19, v18
	v_cvt_pk_bf16_f32 v53, v25, v26
	v_exp_f32_e32 v24, v24
	v_sub_f32_e32 v25, v88, v154
	v_add_f32_e32 v18, v20, v18
	v_exp_f32_e32 v25, v25
	v_sub_f32_e32 v26, v89, v154
	v_add_f32_e32 v18, v21, v18
	v_cvt_pk_bf16_f32 v54, v27, v28
	v_exp_f32_e32 v26, v26
	v_sub_f32_e32 v27, v90, v154
	v_add_f32_e32 v18, v22, v18
	v_exp_f32_e32 v27, v27
	v_sub_f32_e32 v28, v91, v154
	v_add_f32_e32 v18, v23, v18
	v_cvt_pk_bf16_f32 v55, v29, v30
	v_exp_f32_e32 v28, v28
	v_sub_f32_e32 v29, v92, v154
	v_add_f32_e32 v18, v24, v18
	v_exp_f32_e32 v29, v29
	v_sub_f32_e32 v30, v93, v154
	v_add_f32_e32 v18, v25, v18
	v_cvt_pk_bf16_f32 v56, v31, v32
	v_exp_f32_e32 v30, v30
	v_sub_f32_e32 v31, v94, v154
	v_add_f32_e32 v18, v26, v18
	v_exp_f32_e32 v31, v31
	v_sub_f32_e32 v32, v95, v154
	v_add_f32_e32 v18, v27, v18
	v_cvt_pk_bf16_f32 v57, v33, v58
	v_exp_f32_e32 v32, v32
	v_sub_f32_e32 v33, v96, v154
	v_add_f32_e32 v18, v28, v18
	v_exp_f32_e32 v33, v33
	v_sub_f32_e32 v58, v97, v154
	v_add_f32_e32 v18, v29, v18
	v_exp_f32_e32 v66, v58
	v_cvt_pk_bf16_f32 v58, v19, v20
	v_add_f32_e32 v18, v30, v18
	v_sub_f32_e32 v19, v98, v154
	v_add_f32_e32 v18, v31, v18
	v_exp_f32_e32 v19, v19
	v_sub_f32_e32 v20, v99, v154
	v_cvt_pk_bf16_f32 v59, v21, v22
	v_add_f32_e32 v18, v32, v18
	v_exp_f32_e32 v20, v20
	v_sub_f32_e32 v21, v100, v154
	v_add_f32_e32 v18, v33, v18
	v_exp_f32_e32 v21, v21
	v_sub_f32_e32 v22, v101, v154
	v_cvt_pk_bf16_f32 v60, v23, v24
	v_add_f32_e32 v18, v66, v18
	v_exp_f32_e32 v22, v22
	v_sub_f32_e32 v23, v102, v154
	v_exp_f32_e32 v23, v23
	v_sub_f32_e32 v24, v103, v154
	v_add_f32_e32 v18, v19, v18
	v_cvt_pk_bf16_f32 v61, v25, v26
	v_exp_f32_e32 v24, v24
	v_sub_f32_e32 v25, v104, v154
	v_add_f32_e32 v18, v20, v18
	v_exp_f32_e32 v25, v25
	v_sub_f32_e32 v26, v105, v154
	v_add_f32_e32 v18, v21, v18
	v_cvt_pk_bf16_f32 v62, v27, v28
	v_exp_f32_e32 v26, v26
	v_sub_f32_e32 v27, v106, v154
	v_add_f32_e32 v18, v22, v18
	v_exp_f32_e32 v27, v27
	v_sub_f32_e32 v28, v107, v154
	v_add_f32_e32 v18, v23, v18
	v_cvt_pk_bf16_f32 v63, v29, v30
	v_exp_f32_e32 v28, v28
	v_sub_f32_e32 v29, v108, v154
	v_add_f32_e32 v18, v24, v18
	v_exp_f32_e32 v29, v29
	v_sub_f32_e32 v30, v109, v154
	v_add_f32_e32 v18, v25, v18
	v_cvt_pk_bf16_f32 v64, v31, v32
	v_exp_f32_e32 v30, v30
	v_sub_f32_e32 v31, v110, v154
	v_add_f32_e32 v18, v26, v18
	v_exp_f32_e32 v31, v31
	v_sub_f32_e32 v32, v111, v154
	v_add_f32_e32 v18, v27, v18
	v_cvt_pk_bf16_f32 v65, v33, v66
	v_exp_f32_e32 v32, v32
	v_sub_f32_e32 v33, v112, v154
	v_add_f32_e32 v18, v28, v18
	v_exp_f32_e32 v33, v33
	v_sub_f32_e32 v66, v113, v154
	v_add_f32_e32 v18, v29, v18
	v_exp_f32_e32 v74, v66
	v_add_f32_e32 v18, v30, v18
	v_add_f32_e32 v18, v31, v18
	v_add_f32_e32 v18, v32, v18
	v_add_f32_e32 v18, v33, v18
	v_cvt_pk_bf16_f32 v67, v21, v22
	v_add_f32_e32 v22, v74, v18
	v_sub_f32_e32 v18, v114, v154
	v_cvt_pk_bf16_f32 v68, v23, v24
	v_exp_f32_e32 v23, v18
	v_sub_f32_e32 v18, v115, v154
	v_exp_f32_e32 v24, v18
	v_sub_f32_e32 v18, v116, v154
	v_cvt_pk_bf16_f32 v69, v25, v26
	v_exp_f32_e32 v25, v18
	v_sub_f32_e32 v18, v117, v154
	v_exp_f32_e32 v26, v18
	v_sub_f32_e32 v18, v118, v154
	v_cvt_pk_bf16_f32 v70, v27, v28
	v_exp_f32_e32 v27, v18
	v_sub_f32_e32 v18, v119, v154
	v_exp_f32_e32 v28, v18
	v_sub_f32_e32 v18, v120, v154
	v_cvt_pk_bf16_f32 v71, v29, v30
	v_exp_f32_e32 v29, v18
	v_sub_f32_e32 v18, v121, v154
	v_exp_f32_e32 v85, v18
	v_sub_f32_e32 v18, v122, v154
	v_exp_f32_e32 v90, v18
	v_sub_f32_e32 v18, v123, v154
	v_exp_f32_e32 v91, v18
	v_sub_f32_e32 v18, v124, v154
	v_exp_f32_e32 v92, v18
	v_sub_f32_e32 v18, v125, v154
	v_exp_f32_e32 v93, v18
	v_sub_f32_e32 v18, v126, v154
	v_exp_f32_e32 v94, v18
	v_sub_f32_e32 v18, v127, v154
	v_exp_f32_e32 v82, v18
	v_sub_f32_e32 v18, v128, v154
	v_exp_f32_e32 v83, v18
	v_sub_f32_e32 v18, v129, v154
	v_exp_f32_e32 v84, v18
	v_mul_u32_u24_e32 v18, 0x210, v216
	v_add3_u32 v99, 0, v18, v218
	v_cvt_pk_bf16_f32 v66, v19, v20
	ds_read_b128 v[18:21], v99
	ds_read_b128 v[86:89], v99 offset:32
	v_add_f32_e32 v22, v23, v22
	v_add_f32_e32 v22, v24, v22
	v_add_f32_e32 v22, v25, v22
	v_add_f32_e32 v22, v26, v22
	v_add_f32_e32 v22, v27, v22
	v_add_f32_e32 v22, v28, v22
	v_cvt_pk_bf16_f32 v72, v31, v32
	v_cvt_pk_bf16_f32 v73, v33, v74
	v_cvt_pk_bf16_f32 v74, v23, v24
	v_cvt_pk_bf16_f32 v75, v25, v26
	v_cvt_pk_bf16_f32 v76, v27, v28
	v_cvt_pk_bf16_f32 v77, v29, v85
	v_add_f32_e32 v95, v29, v22
	s_waitcnt lgkmcnt(1)
	v_mfma_f32_32x32x16_bf16 v[18:33], v[18:21], v[130:133], 0
	v_add_f32_e32 v85, v85, v95
	v_add_f32_e32 v85, v90, v85
	v_add_f32_e32 v85, v91, v85
	v_add_f32_e32 v85, v92, v85
	v_cvt_pk_bf16_f32 v78, v90, v91
	v_cvt_pk_bf16_f32 v79, v92, v93
	v_add_f32_e32 v85, v93, v85
	ds_read_b128 v[90:93], v99 offset:64
	s_waitcnt lgkmcnt(1)
; #define XLAS __attribute__((address_space(3)))
; __device__ __forceinline__ unsigned cvtpk(float lo, float hi) { f32x2_t v = {lo, hi}; bf16x2_t b = __builtin_convertvector(v, bf16x2_t); return __builtin_bit_cast(unsigned, b); }
; __device__ __forceinline__ void unit(XLAS unsigned char* lds, const bf16_t* Qg, const bf16_t* Kg, const bf16_t* Vg, bf16_t* Og) {
;     ...
;         for (int r = 0; r < 16; ++r) { p[r] = __builtin_amdgcn_exp2f(S[c][r] - mx); l += p[r]; }
; #pragma unroll
;         for (int s = 0; s < 2; ++s) { pw[c][s].x = cvtpk(p[8 * s + 0], p[8 * s + 1]); pw[c][s].y = cvtpk(p[8 * s + 2], p[8 * s + 3]); pw[c][s].z = cvtpk(p[8 * s + 4], p[8 * s + 5]); pw[c][s].w = cvtpk(p[8 * s + 6], p[8 * s + 7]); }
;     }
;     l += __shfl_xor(l, 32);
;     const float rl = 1.0f / l;
;     bf16_t* obase = Og + (size_t)(wid * 32 + (lane >> 3)) * 1024 + (lane & 7) * 8;
; #pragma unroll
;     for (int db = 0; db < 8; ++db) {
;         XLAS unsigned char* buf = lds + (db & 1) * CHB;
;         *(XLAS u32x4*)(buf + wofs) = g[db & 1][0]; *(XLAS u32x4*)(buf + wofs + 16) = g[db & 1][1];
;         __syncthreads();
;         if (db < 6) { g[db & 1][0] = *(const u32x4*)(XAT_SRC(db + 10)); g[db & 1][1] = *(const u32x4*)(XAT_SRC(db + 10) + 8); }
;         f32x16 o = {};
; #pragma unroll
;         for (int kb = 0; kb < 8; ++kb)
; #pragma unroll
;             for (int s = 0; s < 2; ++s) { const bf16x8 vf = *(const XLAS bf16x8*)(buf + vro + kb * 64 + s * 32); o = __builtin_amdgcn_mfma_f32_32x32x16_bf16(vf, __builtin_bit_cast(bf16x8, pw[kb][s]), o, 0, 0, 0); }
; #pragma unroll
;         for (int g4 = 0; g4 < 4; ++g4) { u32x2 w; w.x = cvtpk(o[4 * g4] * rl, o[4 * g4 + 1] * rl); w.y = cvtpk(o[4 * g4 + 2] * rl, o[4 * g4 + 3] * rl);
;             *(XLAS u32x2*)(xs + r32 * 144 + ((db & 1) * 32 + 8 * g4 + 4 * hi) * 2) = w; }
	v_mfma_f32_32x32x16_bf16 v[18:33], v[86:89], v[134:137], v[18:33]
	v_add_f32_e32 v85, v94, v85
	v_cvt_pk_bf16_f32 v80, v94, v82
	v_add_f32_e32 v82, v82, v85
	v_add_f32_e32 v82, v83, v82
	v_cvt_pk_bf16_f32 v81, v83, v84
	v_add_f32_e32 v88, v84, v82
	ds_read_b128 v[82:85], v99 offset:96
	s_waitcnt lgkmcnt(1)
	v_mfma_f32_32x32x16_bf16 v[18:33], v[90:93], v[34:37], v[18:33]
	v_sub_f32_e32 v2, v2, v154
	v_exp_f32_e32 v89, v2
	v_sub_f32_e32 v2, v3, v154
	v_exp_f32_e32 v90, v2
	v_sub_f32_e32 v2, v4, v154
	v_exp_f32_e32 v91, v2
	v_sub_f32_e32 v2, v5, v154
	v_exp_f32_e32 v92, v2
	ds_read_b128 v[2:5], v99 offset:128
	s_waitcnt lgkmcnt(1)
	v_mfma_f32_32x32x16_bf16 v[18:33], v[82:85], v[38:41], v[18:33]
	v_sub_f32_e32 v6, v6, v154
	v_exp_f32_e32 v82, v6
	v_sub_f32_e32 v6, v7, v154
	v_exp_f32_e32 v83, v6
	v_sub_f32_e32 v6, v8, v154
	v_exp_f32_e32 v84, v6
	v_sub_f32_e32 v85, v9, v154
	ds_read_b128 v[6:9], v99 offset:160
	s_waitcnt lgkmcnt(1)
	v_mfma_f32_32x32x16_bf16 v[18:33], v[2:5], v[42:45], v[18:33]
	v_sub_f32_e32 v2, v10, v154
	v_exp_f32_e32 v10, v2
	v_sub_f32_e32 v2, v11, v154
	v_exp_f32_e32 v11, v2
	ds_read_b128 v[2:5], v99 offset:192
	v_exp_f32_e32 v85, v85
	v_sub_f32_e32 v12, v12, v154
	s_waitcnt lgkmcnt(1)
	v_mfma_f32_32x32x16_bf16 v[18:33], v[6:9], v[46:49], v[18:33]
	v_sub_f32_e32 v6, v13, v154
	v_exp_f32_e32 v13, v6
	v_sub_f32_e32 v6, v14, v154
	v_exp_f32_e32 v14, v6
	ds_read_b128 v[6:9], v99 offset:224
	v_exp_f32_e32 v12, v12
	v_sub_f32_e32 v15, v15, v154
	s_waitcnt lgkmcnt(1)
	v_mfma_f32_32x32x16_bf16 v[18:33], v[2:5], v[50:53], v[18:33]
	v_sub_f32_e32 v2, v16, v154
	v_exp_f32_e32 v16, v2
	v_sub_f32_e32 v2, v17, v154
	v_exp_f32_e32 v17, v2
	ds_read_b128 v[2:5], v99 offset:256
	v_exp_f32_e32 v15, v15
	v_cvt_pk_bf16_f32 v86, v89, v90
	s_waitcnt lgkmcnt(1)
	v_mfma_f32_32x32x16_bf16 v[18:33], v[6:9], v[54:57], v[18:33]
	v_add_f32_e32 v6, v89, v88
	v_add_f32_e32 v6, v90, v6
	v_add_f32_e32 v6, v91, v6
	v_add_f32_e32 v6, v92, v6
	v_add_f32_e32 v88, v82, v6
	ds_read_b128 v[6:9], v99 offset:288
	v_cvt_pk_bf16_f32 v87, v91, v92
	s_waitcnt lgkmcnt(1)
	v_mfma_f32_32x32x16_bf16 v[18:33], v[2:5], v[58:61], v[18:33]
	v_add_f32_e32 v2, v83, v88
	v_add_f32_e32 v2, v84, v2
	v_add_f32_e32 v2, v85, v2
	v_add_f32_e32 v2, v10, v2
	v_add_f32_e32 v2, v11, v2
	v_add_f32_e32 v88, v12, v2
	ds_read_b128 v[2:5], v99 offset:320
	s_waitcnt lgkmcnt(1)
	v_mfma_f32_32x32x16_bf16 v[18:33], v[6:9], v[62:65], v[18:33]
	v_add_f32_e32 v6, v13, v88
	v_add_f32_e32 v6, v14, v6
	v_add_f32_e32 v6, v15, v6
	v_add_f32_e32 v6, v16, v6
	v_add_f32_e32 v90, v17, v6
	ds_read_b128 v[6:9], v99 offset:352
	ds_bpermute_b32 v0, v0, v90
	s_waitcnt lgkmcnt(2)
	v_mfma_f32_32x32x16_bf16 v[18:33], v[2:5], v[66:69], v[18:33]
	ds_read_b128 v[2:5], v99 offset:384
	v_cvt_pk_bf16_f32 v88, v82, v83
	v_cvt_pk_bf16_f32 v82, v10, v11
	s_waitcnt lgkmcnt(1)
	v_add_f32_e32 v0, v90, v0
	v_div_scale_f32 v10, s[8:9], v0, v0, 1.0
	v_rcp_f32_e32 v11, v10
	v_mfma_f32_32x32x16_bf16 v[18:33], v[6:9], v[70:73], v[18:33]
	v_cvt_pk_bf16_f32 v83, v12, v13
	v_cvt_pk_bf16_f32 v89, v84, v85
	v_fma_f32 v6, -v10, v11, 1.0
	v_fmac_f32_e32 v11, v6, v11
	ds_read_b128 v[6:9], v99 offset:416
	v_cvt_pk_bf16_f32 v84, v14, v15
	v_cvt_pk_bf16_f32 v85, v16, v17
	s_waitcnt lgkmcnt(1)
	v_mfma_f32_32x32x16_bf16 v[18:33], v[2:5], v[74:77], v[18:33]
	v_div_scale_f32 v2, vcc, 1.0, v0, 1.0
	v_mul_f32_e32 v12, v2, v11
	v_fma_f32 v3, -v10, v12, v2
	v_fmac_f32_e32 v12, v3, v11
	v_fma_f32 v10, -v10, v12, v2
	ds_read_b128 v[2:5], v99 offset:448
	s_waitcnt lgkmcnt(1)
	v_mfma_f32_32x32x16_bf16 v[18:33], v[6:9], v[78:81], v[18:33]
	v_div_fmas_f32 v6, v10, v11, v12
	v_div_fixup_f32 v98, v6, v0, 1.0
	v_mul_u32_u24_e32 v0, 0x90, v216
	v_lshlrev_b32_e32 v6, 3, v217
	v_add3_u32 v0, s16, v0, v6
	ds_read_b128 v[6:9], v99 offset:480
	v_add_u32_e32 v100, 0x8800, v0
	s_waitcnt lgkmcnt(1)
	v_mfma_f32_32x32x16_bf16 v[18:33], v[2:5], v[86:89], v[18:33]
	v_add_co_u32_e32 v4, vcc, s46, v212
	v_lshl_add_u64 v[2:3], v[212:213], 0, s[34:35]
	s_nop 0
	v_addc_co_u32_e32 v5, vcc, 0, v213, vcc
	global_load_dwordx4 v[94:97], v[4:5], off
	global_load_dwordx4 v[90:93], v[2:3], off offset:16
	v_lshlrev_b32_e32 v0, 4, v215
	s_waitcnt lgkmcnt(0)
	v_mfma_f32_32x32x16_bf16 v[18:33], v[6:9], v[82:85], v[18:33]
	v_and_b32_e32 v0, 0x70, v0
	s_addc_u32 s49, s49, s15
	s_nop 9
	v_pk_mul_f32 v[2:3], v[18:19], v[98:99] op_sel_hi:[1,0]
	v_pk_mul_f32 v[4:5], v[20:21], v[98:99] op_sel_hi:[1,0]
	v_cvt_pk_bf16_f32 v2, v2, v3
	v_cvt_pk_bf16_f32 v3, v4, v5
	v_pk_mul_f32 v[4:5], v[22:23], v[98:99] op_sel_hi:[1,0]
	v_pk_mul_f32 v[6:7], v[24:25], v[98:99] op_sel_hi:[1,0]
	v_cvt_pk_bf16_f32 v4, v4, v5
	v_cvt_pk_bf16_f32 v5, v6, v7
	ds_write2_b64 v100, v[2:3], v[4:5] offset1:2
	v_pk_mul_f32 v[2:3], v[26:27], v[98:99] op_sel_hi:[1,0]
	v_pk_mul_f32 v[4:5], v[28:29], v[98:99] op_sel_hi:[1,0]
	v_cvt_pk_bf16_f32 v2, v2, v3
	v_cvt_pk_bf16_f32 v3, v4, v5
	v_pk_mul_f32 v[4:5], v[30:31], v[98:99] op_sel_hi:[1,0]
	v_pk_mul_f32 v[6:7], v[32:33], v[98:99] op_sel_hi:[1,0]
	v_cvt_pk_bf16_f32 v4, v4, v5
	v_cvt_pk_bf16_f32 v5, v6, v7
	ds_write2_b64 v100, v[2:3], v[4:5] offset0:4 offset1:6
	s_waitcnt vmcnt(3)
	ds_write_b128 v214, v[142:145] offset:16896
	s_waitcnt vmcnt(2)
	ds_write_b128 v214, v[138:141] offset:16912
	s_waitcnt lgkmcnt(0)
	s_barrier
; #define XLAS __attribute__((address_space(3)))
; __device__ __forceinline__ unsigned cvtpk(float lo, float hi) { f32x2_t v = {lo, hi}; bf16x2_t b = __builtin_convertvector(v, bf16x2_t); return __builtin_bit_cast(unsigned, b); }
; __device__ __forceinline__ void unit(XLAS unsigned char* lds, const bf16_t* Qg, const bf16_t* Kg, const bf16_t* Vg, bf16_t* Og) {
;     ...
;     for (int db = 0; db < 8; ++db) {
;         XLAS unsigned char* buf = lds + (db & 1) * CHB;
;         *(XLAS u32x4*)(buf + wofs) = g[db & 1][0]; *(XLAS u32x4*)(buf + wofs + 16) = g[db & 1][1];
;         __syncthreads();
;         if (db < 6) { g[db & 1][0] = *(const u32x4*)(XAT_SRC(db + 10)); g[db & 1][1] = *(const u32x4*)(XAT_SRC(db + 10) + 8); }
;         f32x16 o = {};
; #pragma unroll
;         for (int kb = 0; kb < 8; ++kb)
; #pragma unroll
;             for (int s = 0; s < 2; ++s) { const bf16x8 vf = *(const XLAS bf16x8*)(buf + vro + kb * 64 + s * 32); o = __builtin_amdgcn_mfma_f32_32x32x16_bf16(vf, __builtin_bit_cast(bf16x8, pw[kb][s]), o, 0, 0, 0); }
; #pragma unroll
;         for (int g4 = 0; g4 < 4; ++g4) { u32x2 w; w.x = cvtpk(o[4 * g4] * rl, o[4 * g4 + 1] * rl); w.y = cvtpk(o[4 * g4 + 2] * rl, o[4 * g4 + 3] * rl);
;             *(XLAS u32x2*)(xs + r32 * 144 + ((db & 1) * 32 + 8 * g4 + 4 * hi) * 2) = w; }
;         if (db & 1) {
; #pragma unroll
;             for (int i = 0; i < 4; ++i) { const u32x4 v = *(const XLAS u32x4*)(xs + (8 * i + (lane >> 3)) * 144 + (lane & 7) * 16); *(u32x4*)(obase + (size_t)(8 * i) * 1024 + (db >> 1) * 64) = v; }
;         }
	ds_read_b128 v[140:143], v99 offset:16896
	ds_read_b128 v[144:147], v99 offset:16928
	ds_read_b128 v[148:151], v99 offset:16960
	ds_read_b128 v[152:155], v99 offset:16992
	ds_read_b128 v[156:159], v99 offset:17024
	ds_read_b128 v[160:163], v99 offset:17056
	ds_read_b128 v[164:167], v99 offset:17088
	ds_read_b128 v[168:171], v99 offset:17120
	s_waitcnt lgkmcnt(7)
	v_mfma_f32_32x32x16_bf16 v[2:17], v[140:143], v[130:133], 0
	ds_read_b128 v[140:143], v99 offset:17152
	v_bfe_u32 v28, v215, 3, 3
	v_or_b32_e32 v26, s26, v28
	v_ashrrev_i32_e32 v27, 31, v26
	s_waitcnt lgkmcnt(7)
	v_mfma_f32_32x32x16_bf16 v[2:17], v[144:147], v[134:137], v[2:17]
	ds_read_b128 v[144:147], v99 offset:17184
	s_waitcnt lgkmcnt(7)
	v_mfma_f32_32x32x16_bf16 v[2:17], v[148:151], v[34:37], v[2:17]
	ds_read_b128 v[148:151], v99 offset:17216
	s_waitcnt lgkmcnt(7)
	v_mfma_f32_32x32x16_bf16 v[2:17], v[152:155], v[38:41], v[2:17]
	ds_read_b128 v[152:155], v99 offset:17248
	s_waitcnt lgkmcnt(7)
	v_mfma_f32_32x32x16_bf16 v[2:17], v[156:159], v[42:45], v[2:17]
	ds_read_b128 v[156:159], v99 offset:17280
	s_waitcnt lgkmcnt(7)
	v_mfma_f32_32x32x16_bf16 v[2:17], v[160:163], v[46:49], v[2:17]
	ds_read_b128 v[160:163], v99 offset:17312
	s_waitcnt lgkmcnt(7)
	v_mfma_f32_32x32x16_bf16 v[2:17], v[164:167], v[50:53], v[2:17]
	ds_read_b128 v[164:167], v99 offset:17344
	s_waitcnt lgkmcnt(7)
	v_mfma_f32_32x32x16_bf16 v[2:17], v[168:171], v[54:57], v[2:17]
	ds_read_b128 v[168:171], v99 offset:17376
	s_waitcnt lgkmcnt(7)
	v_mfma_f32_32x32x16_bf16 v[2:17], v[140:143], v[58:61], v[2:17]
	s_waitcnt lgkmcnt(6)
	v_mfma_f32_32x32x16_bf16 v[2:17], v[144:147], v[62:65], v[2:17]
	s_waitcnt lgkmcnt(5)
	v_mfma_f32_32x32x16_bf16 v[2:17], v[148:151], v[66:69], v[2:17]
	s_waitcnt lgkmcnt(4)
	v_mfma_f32_32x32x16_bf16 v[2:17], v[152:155], v[70:73], v[2:17]
	s_waitcnt lgkmcnt(3)
	v_mfma_f32_32x32x16_bf16 v[2:17], v[156:159], v[74:77], v[2:17]
	s_waitcnt lgkmcnt(2)
	v_mfma_f32_32x32x16_bf16 v[2:17], v[160:163], v[78:81], v[2:17]
	s_waitcnt lgkmcnt(1)
	v_mfma_f32_32x32x16_bf16 v[2:17], v[164:167], v[86:89], v[2:17]
	v_lshlrev_b64 v[18:19], 11, v[26:27]
	v_lshl_add_u64 v[18:19], s[4:5], 0, v[18:19]
	v_lshl_add_u64 v[26:27], v[18:19], 0, v[0:1]
	v_lshl_add_u64 v[18:19], v[212:213], 0, s[36:37]
	s_mov_b64 s[4:5], 0
	s_waitcnt lgkmcnt(0)
	v_mfma_f32_32x32x16_bf16 v[2:17], v[168:171], v[82:85], v[2:17]
	s_waitcnt vmcnt(1)
	ds_write_b128 v214, v[94:97]
	s_waitcnt vmcnt(0)
	ds_write_b128 v214, v[90:93] offset:16
	s_waitcnt lgkmcnt(0)
	s_barrier
	ds_read_b128 v[140:143], v99
	ds_read_b128 v[144:147], v99 offset:32
	ds_read_b128 v[148:151], v99 offset:64
	ds_read_b128 v[152:155], v99 offset:96
	ds_read_b128 v[156:159], v99 offset:128
	ds_read_b128 v[160:163], v99 offset:160
	ds_read_b128 v[164:167], v99 offset:192
	ds_read_b128 v[168:171], v99 offset:224
	s_nop 11
	v_pk_mul_f32 v[2:3], v[2:3], v[98:99] op_sel_hi:[1,0]
	v_pk_mul_f32 v[4:5], v[4:5], v[98:99] op_sel_hi:[1,0]
	v_cvt_pk_bf16_f32 v2, v2, v3
	v_cvt_pk_bf16_f32 v3, v4, v5
	v_pk_mul_f32 v[4:5], v[6:7], v[98:99] op_sel_hi:[1,0]
	v_pk_mul_f32 v[6:7], v[8:9], v[98:99] op_sel_hi:[1,0]
	v_cvt_pk_bf16_f32 v4, v4, v5
	v_cvt_pk_bf16_f32 v5, v6, v7
	ds_write2_b64 v100, v[2:3], v[4:5] offset0:8 offset1:10
	v_pk_mul_f32 v[2:3], v[10:11], v[98:99] op_sel_hi:[1,0]
	v_pk_mul_f32 v[4:5], v[12:13], v[98:99] op_sel_hi:[1,0]
	v_cvt_pk_bf16_f32 v2, v2, v3
	v_cvt_pk_bf16_f32 v3, v4, v5
	v_pk_mul_f32 v[4:5], v[14:15], v[98:99] op_sel_hi:[1,0]
	v_pk_mul_f32 v[6:7], v[16:17], v[98:99] op_sel_hi:[1,0]
	v_cvt_pk_bf16_f32 v4, v4, v5
	v_cvt_pk_bf16_f32 v5, v6, v7
	ds_write2_b64 v100, v[2:3], v[4:5] offset0:12 offset1:14
	v_mul_u32_u24_e32 v2, 0x90, v28
	v_add_co_u32_e32 v6, vcc, s47, v212
	v_add3_u32 v0, s16, v0, v2
	s_nop 0
	v_addc_co_u32_e32 v7, vcc, 0, v213, vcc
	ds_read_b128 v[2:5], v0 offset:34816
	global_load_dwordx4 v[102:105], v[6:7], off
	global_load_dwordx4 v[106:109], v[18:19], off offset:16
	ds_read_b128 v[6:9], v0 offset:35968
	v_add_co_u32_e32 v28, vcc, s28, v26
	s_waitcnt lgkmcnt(1)
	global_store_dwordx4 v[26:27], v[2:5], off
	v_addc_co_u32_e32 v29, vcc, 0, v27, vcc
	ds_read_b128 v[2:5], v0 offset:37120
	s_waitcnt lgkmcnt(1)
	global_store_dwordx4 v[28:29], v[6:9], off
	ds_read_b128 v[6:9], v0 offset:38272
	v_add_co_u32_e32 v30, vcc, s29, v26
	s_nop 1
	v_addc_co_u32_e32 v31, vcc, 0, v27, vcc
	v_add_co_u32_e32 v32, vcc, s42, v26
	s_waitcnt lgkmcnt(1)
	global_store_dwordx4 v[30:31], v[2:5], off
	v_addc_co_u32_e32 v33, vcc, 0, v27, vcc
	s_waitcnt lgkmcnt(0)
	global_store_dwordx4 v[32:33], v[6:9], off
	s_nop 1
	s_waitcnt lgkmcnt(7)
	v_mfma_f32_32x32x16_bf16 v[2:17], v[140:143], v[130:133], 0
	ds_read_b128 v[140:143], v99 offset:256
	s_waitcnt lgkmcnt(7)
	v_mfma_f32_32x32x16_bf16 v[2:17], v[144:147], v[134:137], v[2:17]
	ds_read_b128 v[144:147], v99 offset:288
	s_waitcnt lgkmcnt(7)
	v_mfma_f32_32x32x16_bf16 v[2:17], v[148:151], v[34:37], v[2:17]
	ds_read_b128 v[148:151], v99 offset:320
	s_waitcnt lgkmcnt(7)
	v_mfma_f32_32x32x16_bf16 v[2:17], v[152:155], v[38:41], v[2:17]
	ds_read_b128 v[152:155], v99 offset:352
	s_waitcnt lgkmcnt(7)
	v_mfma_f32_32x32x16_bf16 v[2:17], v[156:159], v[42:45], v[2:17]
	ds_read_b128 v[156:159], v99 offset:384
	s_waitcnt lgkmcnt(7)
	v_mfma_f32_32x32x16_bf16 v[2:17], v[160:163], v[46:49], v[2:17]
	ds_read_b128 v[160:163], v99 offset:416
	s_waitcnt lgkmcnt(7)
	v_mfma_f32_32x32x16_bf16 v[2:17], v[164:167], v[50:53], v[2:17]
	ds_read_b128 v[164:167], v99 offset:448
	s_waitcnt lgkmcnt(7)
	v_mfma_f32_32x32x16_bf16 v[2:17], v[168:171], v[54:57], v[2:17]
	ds_read_b128 v[168:171], v99 offset:480
	s_waitcnt lgkmcnt(7)
	v_mfma_f32_32x32x16_bf16 v[2:17], v[140:143], v[58:61], v[2:17]
	s_waitcnt lgkmcnt(6)
	v_mfma_f32_32x32x16_bf16 v[2:17], v[144:147], v[62:65], v[2:17]
	s_waitcnt lgkmcnt(5)
	v_mfma_f32_32x32x16_bf16 v[2:17], v[148:151], v[66:69], v[2:17]
	s_waitcnt lgkmcnt(4)
	v_mfma_f32_32x32x16_bf16 v[2:17], v[152:155], v[70:73], v[2:17]
	s_waitcnt lgkmcnt(3)
	v_mfma_f32_32x32x16_bf16 v[2:17], v[156:159], v[74:77], v[2:17]
	s_waitcnt lgkmcnt(2)
	v_mfma_f32_32x32x16_bf16 v[2:17], v[160:163], v[78:81], v[2:17]
	s_waitcnt lgkmcnt(1)
	v_mfma_f32_32x32x16_bf16 v[2:17], v[164:167], v[86:89], v[2:17]
	v_add_co_u32_e32 v20, vcc, s17, v212
	v_lshl_add_u64 v[18:19], v[212:213], 0, s[30:31]
	s_nop 0
	v_addc_co_u32_e32 v21, vcc, 0, v213, vcc
	global_load_dwordx4 v[22:25], v[20:21], off
	s_nop 0
	global_load_dwordx4 v[18:21], v[18:19], off offset:16
	s_waitcnt lgkmcnt(0)
	v_mfma_f32_32x32x16_bf16 v[2:17], v[168:171], v[82:85], v[2:17]
	s_waitcnt vmcnt(7)
	ds_write_b128 v214, v[102:105] offset:16896
	s_waitcnt vmcnt(6)
	ds_write_b128 v214, v[106:109] offset:16912
	s_waitcnt lgkmcnt(0)
	s_barrier
; #define XLAS __attribute__((address_space(3)))
; __device__ __forceinline__ unsigned cvtpk(float lo, float hi) { f32x2_t v = {lo, hi}; bf16x2_t b = __builtin_convertvector(v, bf16x2_t); return __builtin_bit_cast(unsigned, b); }
; __device__ __forceinline__ void unit(XLAS unsigned char* lds, const bf16_t* Qg, const bf16_t* Kg, const bf16_t* Vg, bf16_t* Og) {
;     ...
;     for (int db = 0; db < 8; ++db) {
;         XLAS unsigned char* buf = lds + (db & 1) * CHB;
;         *(XLAS u32x4*)(buf + wofs) = g[db & 1][0]; *(XLAS u32x4*)(buf + wofs + 16) = g[db & 1][1];
;         __syncthreads();
;         if (db < 6) { g[db & 1][0] = *(const u32x4*)(XAT_SRC(db + 10)); g[db & 1][1] = *(const u32x4*)(XAT_SRC(db + 10) + 8); }
;         f32x16 o = {};
; #pragma unroll
;         for (int kb = 0; kb < 8; ++kb)
; #pragma unroll
;             for (int s = 0; s < 2; ++s) { const bf16x8 vf = *(const XLAS bf16x8*)(buf + vro + kb * 64 + s * 32); o = __builtin_amdgcn_mfma_f32_32x32x16_bf16(vf, __builtin_bit_cast(bf16x8, pw[kb][s]), o, 0, 0, 0); }
; #pragma unroll
;         for (int g4 = 0; g4 < 4; ++g4) { u32x2 w; w.x = cvtpk(o[4 * g4] * rl, o[4 * g4 + 1] * rl); w.y = cvtpk(o[4 * g4 + 2] * rl, o[4 * g4 + 3] * rl);
;             *(XLAS u32x2*)(xs + r32 * 144 + ((db & 1) * 32 + 8 * g4 + 4 * hi) * 2) = w; }
;         if (db & 1) {
; #pragma unroll
;             for (int i = 0; i < 4; ++i) { const u32x4 v = *(const XLAS u32x4*)(xs + (8 * i + (lane >> 3)) * 144 + (lane & 7) * 16); *(u32x4*)(obase + (size_t)(8 * i) * 1024 + (db >> 1) * 64) = v; }
;         }
	ds_read_b128 v[140:143], v99 offset:16896
	ds_read_b128 v[144:147], v99 offset:16928
	ds_read_b128 v[148:151], v99 offset:16960
	ds_read_b128 v[152:155], v99 offset:16992
	ds_read_b128 v[156:159], v99 offset:17024
	ds_read_b128 v[160:163], v99 offset:17056
	ds_read_b128 v[164:167], v99 offset:17088
	ds_read_b128 v[168:171], v99 offset:17120
	s_nop 11
	v_pk_mul_f32 v[2:3], v[2:3], v[98:99] op_sel_hi:[1,0]
	v_pk_mul_f32 v[4:5], v[4:5], v[98:99] op_sel_hi:[1,0]
	v_cvt_pk_bf16_f32 v2, v2, v3
	v_cvt_pk_bf16_f32 v3, v4, v5
	v_pk_mul_f32 v[4:5], v[6:7], v[98:99] op_sel_hi:[1,0]
	v_pk_mul_f32 v[6:7], v[8:9], v[98:99] op_sel_hi:[1,0]
	v_cvt_pk_bf16_f32 v4, v4, v5
	v_cvt_pk_bf16_f32 v5, v6, v7
	ds_write2_b64 v100, v[2:3], v[4:5] offset1:2
	v_pk_mul_f32 v[2:3], v[10:11], v[98:99] op_sel_hi:[1,0]
	v_pk_mul_f32 v[4:5], v[12:13], v[98:99] op_sel_hi:[1,0]
	v_cvt_pk_bf16_f32 v2, v2, v3
	v_cvt_pk_bf16_f32 v3, v4, v5
	v_pk_mul_f32 v[4:5], v[14:15], v[98:99] op_sel_hi:[1,0]
	v_pk_mul_f32 v[6:7], v[16:17], v[98:99] op_sel_hi:[1,0]
	v_cvt_pk_bf16_f32 v4, v4, v5
	v_cvt_pk_bf16_f32 v5, v6, v7
	ds_write2_b64 v100, v[2:3], v[4:5] offset0:4 offset1:6
	s_nop 1
	s_waitcnt lgkmcnt(7)
	v_mfma_f32_32x32x16_bf16 v[2:17], v[140:143], v[130:133], 0
	ds_read_b128 v[140:143], v99 offset:17152
	v_lshl_add_u64 v[102:103], v[212:213], 0, s[38:39]
	s_waitcnt lgkmcnt(7)
	v_mfma_f32_32x32x16_bf16 v[2:17], v[144:147], v[134:137], v[2:17]
	ds_read_b128 v[144:147], v99 offset:17184
	s_waitcnt lgkmcnt(7)
	v_mfma_f32_32x32x16_bf16 v[2:17], v[148:151], v[34:37], v[2:17]
	ds_read_b128 v[148:151], v99 offset:17216
	s_waitcnt lgkmcnt(7)
	v_mfma_f32_32x32x16_bf16 v[2:17], v[152:155], v[38:41], v[2:17]
	ds_read_b128 v[152:155], v99 offset:17248
	s_waitcnt lgkmcnt(7)
	v_mfma_f32_32x32x16_bf16 v[2:17], v[156:159], v[42:45], v[2:17]
	ds_read_b128 v[156:159], v99 offset:17280
	s_waitcnt lgkmcnt(7)
	v_mfma_f32_32x32x16_bf16 v[2:17], v[160:163], v[46:49], v[2:17]
	ds_read_b128 v[160:163], v99 offset:17312
	s_waitcnt lgkmcnt(7)
	v_mfma_f32_32x32x16_bf16 v[2:17], v[164:167], v[50:53], v[2:17]
	ds_read_b128 v[164:167], v99 offset:17344
	s_waitcnt lgkmcnt(7)
	v_mfma_f32_32x32x16_bf16 v[2:17], v[168:171], v[54:57], v[2:17]
	ds_read_b128 v[168:171], v99 offset:17376
	s_waitcnt lgkmcnt(7)
	v_mfma_f32_32x32x16_bf16 v[2:17], v[140:143], v[58:61], v[2:17]
	s_waitcnt lgkmcnt(6)
	v_mfma_f32_32x32x16_bf16 v[2:17], v[144:147], v[62:65], v[2:17]
	s_waitcnt lgkmcnt(5)
	v_mfma_f32_32x32x16_bf16 v[2:17], v[148:151], v[66:69], v[2:17]
	s_waitcnt lgkmcnt(4)
	v_mfma_f32_32x32x16_bf16 v[2:17], v[152:155], v[70:73], v[2:17]
	s_waitcnt lgkmcnt(3)
	v_mfma_f32_32x32x16_bf16 v[2:17], v[156:159], v[74:77], v[2:17]
	s_waitcnt lgkmcnt(2)
	v_mfma_f32_32x32x16_bf16 v[2:17], v[160:163], v[78:81], v[2:17]
	s_waitcnt lgkmcnt(1)
	v_mfma_f32_32x32x16_bf16 v[2:17], v[164:167], v[86:89], v[2:17]
	v_add_co_u32_e32 v90, vcc, s27, v212
	s_nop 1
	v_addc_co_u32_e32 v91, vcc, 0, v213, vcc
	s_waitcnt lgkmcnt(0)
	v_mfma_f32_32x32x16_bf16 v[2:17], v[168:171], v[82:85], v[2:17]
	s_waitcnt vmcnt(1)
	ds_write_b128 v214, v[22:25]
	s_waitcnt vmcnt(0)
	ds_write_b128 v214, v[18:21] offset:16
	s_waitcnt lgkmcnt(0)
	s_barrier
	ds_read_b128 v[140:143], v99
	ds_read_b128 v[144:147], v99 offset:32
	ds_read_b128 v[148:151], v99 offset:64
	ds_read_b128 v[152:155], v99 offset:96
	ds_read_b128 v[156:159], v99 offset:128
	ds_read_b128 v[160:163], v99 offset:160
	ds_read_b128 v[164:167], v99 offset:192
	ds_read_b128 v[168:171], v99 offset:224
	s_nop 11
	v_pk_mul_f32 v[2:3], v[98:99], v[2:3] op_sel_hi:[0,1]
	v_pk_mul_f32 v[4:5], v[98:99], v[4:5] op_sel_hi:[0,1]
	v_cvt_pk_bf16_f32 v2, v2, v3
	v_cvt_pk_bf16_f32 v3, v4, v5
	v_pk_mul_f32 v[4:5], v[98:99], v[6:7] op_sel_hi:[0,1]
	v_pk_mul_f32 v[6:7], v[98:99], v[8:9] op_sel_hi:[0,1]
	v_cvt_pk_bf16_f32 v4, v4, v5
	v_cvt_pk_bf16_f32 v5, v6, v7
	ds_write2_b64 v100, v[2:3], v[4:5] offset0:8 offset1:10
	v_pk_mul_f32 v[2:3], v[98:99], v[10:11] op_sel_hi:[0,1]
	v_pk_mul_f32 v[4:5], v[98:99], v[12:13] op_sel_hi:[0,1]
	v_cvt_pk_bf16_f32 v2, v2, v3
	v_cvt_pk_bf16_f32 v3, v4, v5
	v_pk_mul_f32 v[4:5], v[98:99], v[14:15] op_sel_hi:[0,1]
	v_pk_mul_f32 v[6:7], v[98:99], v[16:17] op_sel_hi:[0,1]
	v_cvt_pk_bf16_f32 v4, v4, v5
	v_cvt_pk_bf16_f32 v5, v6, v7
	ds_write2_b64 v100, v[2:3], v[4:5] offset0:12 offset1:14
	ds_read_b128 v[2:5], v0 offset:34816
	ds_read_b128 v[6:9], v0 offset:35968
	ds_read_b128 v[10:13], v0 offset:37120
	ds_read_b128 v[14:17], v0 offset:38272
	global_load_dwordx4 v[90:93], v[90:91], off
	s_nop 0
	global_load_dwordx4 v[94:97], v[102:103], off offset:16
	s_waitcnt lgkmcnt(3)
	global_store_dwordx4 v[26:27], v[2:5], off offset:128
	s_waitcnt lgkmcnt(2)
	global_store_dwordx4 v[28:29], v[6:9], off offset:128
	s_waitcnt lgkmcnt(1)
	global_store_dwordx4 v[30:31], v[10:13], off offset:128
	s_waitcnt lgkmcnt(0)
	global_store_dwordx4 v[32:33], v[14:17], off offset:128
	s_nop 1
	s_waitcnt lgkmcnt(7)
	v_mfma_f32_32x32x16_bf16 v[2:17], v[140:143], v[130:133], 0
	ds_read_b128 v[140:143], v99 offset:256
	s_waitcnt lgkmcnt(7)
	v_mfma_f32_32x32x16_bf16 v[2:17], v[144:147], v[134:137], v[2:17]
	ds_read_b128 v[144:147], v99 offset:288
	s_waitcnt lgkmcnt(7)
	v_mfma_f32_32x32x16_bf16 v[2:17], v[148:151], v[34:37], v[2:17]
	ds_read_b128 v[148:151], v99 offset:320
	s_waitcnt lgkmcnt(7)
	v_mfma_f32_32x32x16_bf16 v[2:17], v[152:155], v[38:41], v[2:17]
	ds_read_b128 v[152:155], v99 offset:352
	s_waitcnt lgkmcnt(7)
	v_mfma_f32_32x32x16_bf16 v[2:17], v[156:159], v[42:45], v[2:17]
	ds_read_b128 v[156:159], v99 offset:384
	s_waitcnt lgkmcnt(7)
	v_mfma_f32_32x32x16_bf16 v[2:17], v[160:163], v[46:49], v[2:17]
	ds_read_b128 v[160:163], v99 offset:416
	s_waitcnt lgkmcnt(7)
	v_mfma_f32_32x32x16_bf16 v[2:17], v[164:167], v[50:53], v[2:17]
	ds_read_b128 v[164:167], v99 offset:448
	s_waitcnt lgkmcnt(7)
	v_mfma_f32_32x32x16_bf16 v[2:17], v[168:171], v[54:57], v[2:17]
	ds_read_b128 v[168:171], v99 offset:480
	s_waitcnt lgkmcnt(7)
	v_mfma_f32_32x32x16_bf16 v[2:17], v[140:143], v[58:61], v[2:17]
	s_waitcnt lgkmcnt(6)
	v_mfma_f32_32x32x16_bf16 v[2:17], v[144:147], v[62:65], v[2:17]
	s_waitcnt lgkmcnt(5)
	v_mfma_f32_32x32x16_bf16 v[2:17], v[148:151], v[66:69], v[2:17]
	s_waitcnt lgkmcnt(4)
	v_mfma_f32_32x32x16_bf16 v[2:17], v[152:155], v[70:73], v[2:17]
	s_waitcnt lgkmcnt(3)
	v_mfma_f32_32x32x16_bf16 v[2:17], v[156:159], v[74:77], v[2:17]
	s_waitcnt lgkmcnt(2)
	v_mfma_f32_32x32x16_bf16 v[2:17], v[160:163], v[78:81], v[2:17]
	s_waitcnt lgkmcnt(1)
	v_mfma_f32_32x32x16_bf16 v[2:17], v[164:167], v[86:89], v[2:17]
	v_add_co_u32_e32 v20, vcc, s58, v212
	v_lshl_add_u64 v[18:19], v[212:213], 0, s[56:57]
	s_nop 0
	v_addc_co_u32_e32 v21, vcc, 0, v213, vcc
	global_load_dwordx4 v[22:25], v[20:21], off
	s_nop 0
	global_load_dwordx4 v[18:21], v[18:19], off offset:16
	s_waitcnt lgkmcnt(0)
	v_mfma_f32_32x32x16_bf16 v[2:17], v[168:171], v[82:85], v[2:17]
	s_waitcnt vmcnt(7)
	ds_write_b128 v214, v[90:93] offset:16896
	s_waitcnt vmcnt(6)
	ds_write_b128 v214, v[94:97] offset:16912
	s_waitcnt lgkmcnt(0)
	s_barrier
; #define XLAS __attribute__((address_space(3)))
; __device__ __forceinline__ unsigned cvtpk(float lo, float hi) { f32x2_t v = {lo, hi}; bf16x2_t b = __builtin_convertvector(v, bf16x2_t); return __builtin_bit_cast(unsigned, b); }
; __device__ __forceinline__ void unit(XLAS unsigned char* lds, const bf16_t* Qg, const bf16_t* Kg, const bf16_t* Vg, bf16_t* Og) {
;     ...
;     for (int db = 0; db < 8; ++db) {
;         XLAS unsigned char* buf = lds + (db & 1) * CHB;
;         *(XLAS u32x4*)(buf + wofs) = g[db & 1][0]; *(XLAS u32x4*)(buf + wofs + 16) = g[db & 1][1];
;         __syncthreads();
;         if (db < 6) { g[db & 1][0] = *(const u32x4*)(XAT_SRC(db + 10)); g[db & 1][1] = *(const u32x4*)(XAT_SRC(db + 10) + 8); }
;         f32x16 o = {};
; #pragma unroll
;         for (int kb = 0; kb < 8; ++kb)
; #pragma unroll
;             for (int s = 0; s < 2; ++s) { const bf16x8 vf = *(const XLAS bf16x8*)(buf + vro + kb * 64 + s * 32); o = __builtin_amdgcn_mfma_f32_32x32x16_bf16(vf, __builtin_bit_cast(bf16x8, pw[kb][s]), o, 0, 0, 0); }
; #pragma unroll
;         for (int g4 = 0; g4 < 4; ++g4) { u32x2 w; w.x = cvtpk(o[4 * g4] * rl, o[4 * g4 + 1] * rl); w.y = cvtpk(o[4 * g4 + 2] * rl, o[4 * g4 + 3] * rl);
;             *(XLAS u32x2*)(xs + r32 * 144 + ((db & 1) * 32 + 8 * g4 + 4 * hi) * 2) = w; }
;         if (db & 1) {
; #pragma unroll
;             for (int i = 0; i < 4; ++i) { const u32x4 v = *(const XLAS u32x4*)(xs + (8 * i + (lane >> 3)) * 144 + (lane & 7) * 16); *(u32x4*)(obase + (size_t)(8 * i) * 1024 + (db >> 1) * 64) = v; }
;         }
	ds_read_b128 v[140:143], v99 offset:16896
	ds_read_b128 v[144:147], v99 offset:16928
	ds_read_b128 v[148:151], v99 offset:16960
	ds_read_b128 v[152:155], v99 offset:16992
	ds_read_b128 v[156:159], v99 offset:17024
	ds_read_b128 v[160:163], v99 offset:17056
	ds_read_b128 v[164:167], v99 offset:17088
	ds_read_b128 v[168:171], v99 offset:17120
	v_lshl_add_u64 v[102:103], v[212:213], 0, s[60:61]
	s_nop 10
	v_pk_mul_f32 v[2:3], v[98:99], v[2:3] op_sel_hi:[0,1]
	v_pk_mul_f32 v[4:5], v[98:99], v[4:5] op_sel_hi:[0,1]
	v_cvt_pk_bf16_f32 v2, v2, v3
	v_cvt_pk_bf16_f32 v3, v4, v5
	v_pk_mul_f32 v[4:5], v[98:99], v[6:7] op_sel_hi:[0,1]
	v_pk_mul_f32 v[6:7], v[98:99], v[8:9] op_sel_hi:[0,1]
	v_cvt_pk_bf16_f32 v4, v4, v5
	v_cvt_pk_bf16_f32 v5, v6, v7
	ds_write2_b64 v100, v[2:3], v[4:5] offset1:2
	v_pk_mul_f32 v[2:3], v[98:99], v[10:11] op_sel_hi:[0,1]
	v_pk_mul_f32 v[4:5], v[98:99], v[12:13] op_sel_hi:[0,1]
	v_cvt_pk_bf16_f32 v2, v2, v3
	v_cvt_pk_bf16_f32 v3, v4, v5
	v_pk_mul_f32 v[4:5], v[98:99], v[14:15] op_sel_hi:[0,1]
	v_pk_mul_f32 v[6:7], v[98:99], v[16:17] op_sel_hi:[0,1]
	v_cvt_pk_bf16_f32 v4, v4, v5
	v_cvt_pk_bf16_f32 v5, v6, v7
	ds_write2_b64 v100, v[2:3], v[4:5] offset0:4 offset1:6
	s_nop 1
	s_waitcnt lgkmcnt(7)
	v_mfma_f32_32x32x16_bf16 v[2:17], v[140:143], v[130:133], 0
	ds_read_b128 v[140:143], v99 offset:17152
	s_waitcnt lgkmcnt(7)
	v_mfma_f32_32x32x16_bf16 v[2:17], v[144:147], v[134:137], v[2:17]
	ds_read_b128 v[144:147], v99 offset:17184
	s_waitcnt lgkmcnt(7)
	v_mfma_f32_32x32x16_bf16 v[2:17], v[148:151], v[34:37], v[2:17]
	ds_read_b128 v[148:151], v99 offset:17216
	s_waitcnt lgkmcnt(7)
	v_mfma_f32_32x32x16_bf16 v[2:17], v[152:155], v[38:41], v[2:17]
	ds_read_b128 v[152:155], v99 offset:17248
	s_waitcnt lgkmcnt(7)
	v_mfma_f32_32x32x16_bf16 v[2:17], v[156:159], v[42:45], v[2:17]
	ds_read_b128 v[156:159], v99 offset:17280
	s_waitcnt lgkmcnt(7)
	v_mfma_f32_32x32x16_bf16 v[2:17], v[160:163], v[46:49], v[2:17]
	ds_read_b128 v[160:163], v99 offset:17312
	s_waitcnt lgkmcnt(7)
	v_mfma_f32_32x32x16_bf16 v[2:17], v[164:167], v[50:53], v[2:17]
	ds_read_b128 v[164:167], v99 offset:17344
	s_waitcnt lgkmcnt(7)
	v_mfma_f32_32x32x16_bf16 v[2:17], v[168:171], v[54:57], v[2:17]
	ds_read_b128 v[168:171], v99 offset:17376
	s_waitcnt lgkmcnt(7)
	v_mfma_f32_32x32x16_bf16 v[2:17], v[140:143], v[58:61], v[2:17]
	s_waitcnt lgkmcnt(6)
	v_mfma_f32_32x32x16_bf16 v[2:17], v[144:147], v[62:65], v[2:17]
	s_waitcnt lgkmcnt(5)
	v_mfma_f32_32x32x16_bf16 v[2:17], v[148:151], v[66:69], v[2:17]
	s_waitcnt lgkmcnt(4)
	v_mfma_f32_32x32x16_bf16 v[2:17], v[152:155], v[70:73], v[2:17]
	s_waitcnt lgkmcnt(3)
	v_mfma_f32_32x32x16_bf16 v[2:17], v[156:159], v[74:77], v[2:17]
	s_waitcnt lgkmcnt(2)
	v_mfma_f32_32x32x16_bf16 v[2:17], v[160:163], v[78:81], v[2:17]
	s_waitcnt lgkmcnt(1)
	v_mfma_f32_32x32x16_bf16 v[2:17], v[164:167], v[86:89], v[2:17]
	v_add_co_u32_e32 v90, vcc, s59, v212
	s_nop 1
	v_addc_co_u32_e32 v91, vcc, 0, v213, vcc
	s_waitcnt lgkmcnt(0)
	v_mfma_f32_32x32x16_bf16 v[2:17], v[168:171], v[82:85], v[2:17]
	s_waitcnt vmcnt(1)
	ds_write_b128 v214, v[22:25]
	s_waitcnt vmcnt(0)
	ds_write_b128 v214, v[18:21] offset:16
	s_waitcnt lgkmcnt(0)
	s_barrier
	ds_read_b128 v[140:143], v99
	ds_read_b128 v[144:147], v99 offset:32
	ds_read_b128 v[148:151], v99 offset:64
	ds_read_b128 v[152:155], v99 offset:96
	ds_read_b128 v[156:159], v99 offset:128
	ds_read_b128 v[160:163], v99 offset:160
	ds_read_b128 v[164:167], v99 offset:192
	ds_read_b128 v[168:171], v99 offset:224
	s_nop 11
	v_pk_mul_f32 v[2:3], v[98:99], v[2:3] op_sel_hi:[0,1]
	v_pk_mul_f32 v[4:5], v[98:99], v[4:5] op_sel_hi:[0,1]
	v_cvt_pk_bf16_f32 v2, v2, v3
	v_cvt_pk_bf16_f32 v3, v4, v5
	v_pk_mul_f32 v[4:5], v[98:99], v[6:7] op_sel_hi:[0,1]
	v_pk_mul_f32 v[6:7], v[98:99], v[8:9] op_sel_hi:[0,1]
	v_cvt_pk_bf16_f32 v4, v4, v5
	v_cvt_pk_bf16_f32 v5, v6, v7
	ds_write2_b64 v100, v[2:3], v[4:5] offset0:8 offset1:10
	v_pk_mul_f32 v[2:3], v[98:99], v[10:11] op_sel_hi:[0,1]
	v_pk_mul_f32 v[4:5], v[98:99], v[12:13] op_sel_hi:[0,1]
	v_cvt_pk_bf16_f32 v2, v2, v3
	v_cvt_pk_bf16_f32 v3, v4, v5
	v_pk_mul_f32 v[4:5], v[98:99], v[14:15] op_sel_hi:[0,1]
	v_pk_mul_f32 v[6:7], v[98:99], v[16:17] op_sel_hi:[0,1]
	v_cvt_pk_bf16_f32 v4, v4, v5
	v_cvt_pk_bf16_f32 v5, v6, v7
	ds_write2_b64 v100, v[2:3], v[4:5] offset0:12 offset1:14
	ds_read_b128 v[2:5], v0 offset:34816
	ds_read_b128 v[6:9], v0 offset:35968
	ds_read_b128 v[10:13], v0 offset:37120
	ds_read_b128 v[14:17], v0 offset:38272
	global_load_dwordx4 v[90:93], v[90:91], off
	s_nop 0
	global_load_dwordx4 v[94:97], v[102:103], off offset:16
	s_waitcnt lgkmcnt(3)
	global_store_dwordx4 v[26:27], v[2:5], off offset:256
	s_waitcnt lgkmcnt(2)
	global_store_dwordx4 v[28:29], v[6:9], off offset:256
	s_waitcnt lgkmcnt(1)
	global_store_dwordx4 v[30:31], v[10:13], off offset:256
	s_waitcnt lgkmcnt(0)
	global_store_dwordx4 v[32:33], v[14:17], off offset:256
	s_nop 1
	s_waitcnt lgkmcnt(7)
	v_mfma_f32_32x32x16_bf16 v[2:17], v[140:143], v[130:133], 0
	ds_read_b128 v[140:143], v99 offset:256
	s_waitcnt lgkmcnt(7)
	v_mfma_f32_32x32x16_bf16 v[2:17], v[144:147], v[134:137], v[2:17]
	ds_read_b128 v[144:147], v99 offset:288
	s_waitcnt lgkmcnt(7)
	v_mfma_f32_32x32x16_bf16 v[2:17], v[148:151], v[34:37], v[2:17]
	ds_read_b128 v[148:151], v99 offset:320
	s_waitcnt lgkmcnt(7)
	v_mfma_f32_32x32x16_bf16 v[2:17], v[152:155], v[38:41], v[2:17]
	ds_read_b128 v[152:155], v99 offset:352
	s_waitcnt lgkmcnt(7)
	v_mfma_f32_32x32x16_bf16 v[2:17], v[156:159], v[42:45], v[2:17]
	ds_read_b128 v[156:159], v99 offset:384
	s_waitcnt lgkmcnt(7)
	v_mfma_f32_32x32x16_bf16 v[2:17], v[160:163], v[46:49], v[2:17]
	ds_read_b128 v[160:163], v99 offset:416
	s_waitcnt lgkmcnt(7)
	v_mfma_f32_32x32x16_bf16 v[2:17], v[164:167], v[50:53], v[2:17]
	ds_read_b128 v[164:167], v99 offset:448
	s_waitcnt lgkmcnt(7)
	v_mfma_f32_32x32x16_bf16 v[2:17], v[168:171], v[54:57], v[2:17]
	ds_read_b128 v[168:171], v99 offset:480
	s_waitcnt lgkmcnt(7)
	v_mfma_f32_32x32x16_bf16 v[2:17], v[140:143], v[58:61], v[2:17]
	s_waitcnt lgkmcnt(6)
	v_mfma_f32_32x32x16_bf16 v[2:17], v[144:147], v[62:65], v[2:17]
	s_waitcnt lgkmcnt(5)
	v_mfma_f32_32x32x16_bf16 v[2:17], v[148:151], v[66:69], v[2:17]
	s_waitcnt lgkmcnt(4)
	v_mfma_f32_32x32x16_bf16 v[2:17], v[152:155], v[70:73], v[2:17]
	s_waitcnt lgkmcnt(3)
	v_mfma_f32_32x32x16_bf16 v[2:17], v[156:159], v[74:77], v[2:17]
	s_waitcnt lgkmcnt(2)
	v_mfma_f32_32x32x16_bf16 v[2:17], v[160:163], v[78:81], v[2:17]
	s_waitcnt lgkmcnt(1)
	v_mfma_f32_32x32x16_bf16 v[2:17], v[164:167], v[86:89], v[2:17]
	s_waitcnt lgkmcnt(0)
	v_mfma_f32_32x32x16_bf16 v[2:17], v[168:171], v[82:85], v[2:17]
	s_waitcnt vmcnt(5)
	ds_write_b128 v214, v[90:93] offset:16896
	s_waitcnt vmcnt(4)
	ds_write_b128 v214, v[94:97] offset:16912
	s_waitcnt lgkmcnt(0)
	s_barrier
; #define XLAS __attribute__((address_space(3)))
; __device__ __forceinline__ unsigned cvtpk(float lo, float hi) { f32x2_t v = {lo, hi}; bf16x2_t b = __builtin_convertvector(v, bf16x2_t); return __builtin_bit_cast(unsigned, b); }
; __device__ __forceinline__ void unit(XLAS unsigned char* lds, const bf16_t* Qg, const bf16_t* Kg, const bf16_t* Vg, bf16_t* Og) {
;     ...
;     for (int db = 0; db < 8; ++db) {
;         XLAS unsigned char* buf = lds + (db & 1) * CHB;
;         *(XLAS u32x4*)(buf + wofs) = g[db & 1][0]; *(XLAS u32x4*)(buf + wofs + 16) = g[db & 1][1];
;         __syncthreads();
;         if (db < 6) { g[db & 1][0] = *(const u32x4*)(XAT_SRC(db + 10)); g[db & 1][1] = *(const u32x4*)(XAT_SRC(db + 10) + 8); }
;         f32x16 o = {};
; #pragma unroll
;         for (int kb = 0; kb < 8; ++kb)
; #pragma unroll
;             for (int s = 0; s < 2; ++s) { const bf16x8 vf = *(const XLAS bf16x8*)(buf + vro + kb * 64 + s * 32); o = __builtin_amdgcn_mfma_f32_32x32x16_bf16(vf, __builtin_bit_cast(bf16x8, pw[kb][s]), o, 0, 0, 0); }
; #pragma unroll
;         for (int g4 = 0; g4 < 4; ++g4) { u32x2 w; w.x = cvtpk(o[4 * g4] * rl, o[4 * g4 + 1] * rl); w.y = cvtpk(o[4 * g4 + 2] * rl, o[4 * g4 + 3] * rl);
;             *(XLAS u32x2*)(xs + r32 * 144 + ((db & 1) * 32 + 8 * g4 + 4 * hi) * 2) = w; }
;         if (db & 1) {
; #pragma unroll
;             for (int i = 0; i < 4; ++i) { const u32x4 v = *(const XLAS u32x4*)(xs + (8 * i + (lane >> 3)) * 144 + (lane & 7) * 16); *(u32x4*)(obase + (size_t)(8 * i) * 1024 + (db >> 1) * 64) = v; }
;         }
	ds_read_b128 v[140:143], v99 offset:16896
	ds_read_b128 v[144:147], v99 offset:16928
	ds_read_b128 v[148:151], v99 offset:16960
	ds_read_b128 v[152:155], v99 offset:16992
	ds_read_b128 v[156:159], v99 offset:17024
	ds_read_b128 v[160:163], v99 offset:17056
	ds_read_b128 v[164:167], v99 offset:17088
	ds_read_b128 v[168:171], v99 offset:17120
	s_nop 11
	v_pk_mul_f32 v[2:3], v[98:99], v[2:3] op_sel_hi:[0,1]
	v_pk_mul_f32 v[4:5], v[98:99], v[4:5] op_sel_hi:[0,1]
	v_pk_mul_f32 v[6:7], v[98:99], v[6:7] op_sel_hi:[0,1]
	v_pk_mul_f32 v[8:9], v[98:99], v[8:9] op_sel_hi:[0,1]
	v_pk_mul_f32 v[10:11], v[98:99], v[10:11] op_sel_hi:[0,1]
	v_pk_mul_f32 v[12:13], v[98:99], v[12:13] op_sel_hi:[0,1]
	v_pk_mul_f32 v[14:15], v[98:99], v[14:15] op_sel_hi:[0,1]
	v_pk_mul_f32 v[16:17], v[98:99], v[16:17] op_sel_hi:[0,1]
	v_cvt_pk_bf16_f32 v2, v2, v3
	v_cvt_pk_bf16_f32 v3, v4, v5
	v_cvt_pk_bf16_f32 v4, v6, v7
	v_cvt_pk_bf16_f32 v5, v8, v9
	v_cvt_pk_bf16_f32 v6, v10, v11
	v_cvt_pk_bf16_f32 v7, v12, v13
	v_cvt_pk_bf16_f32 v8, v14, v15
	v_cvt_pk_bf16_f32 v9, v16, v17
	ds_write2_b64 v100, v[2:3], v[4:5] offset1:2
	ds_write2_b64 v100, v[6:7], v[8:9] offset0:4 offset1:6
	s_nop 1
	s_waitcnt lgkmcnt(7)
	v_mfma_f32_32x32x16_bf16 v[2:17], v[140:143], v[130:133], 0
	ds_read_b128 v[140:143], v99 offset:17152
	s_waitcnt lgkmcnt(7)
	v_mfma_f32_32x32x16_bf16 v[2:17], v[144:147], v[134:137], v[2:17]
	ds_read_b128 v[144:147], v99 offset:17184
	s_waitcnt lgkmcnt(7)
	v_mfma_f32_32x32x16_bf16 v[2:17], v[148:151], v[34:37], v[2:17]
	ds_read_b128 v[148:151], v99 offset:17216
	s_waitcnt lgkmcnt(7)
	v_mfma_f32_32x32x16_bf16 v[2:17], v[152:155], v[38:41], v[2:17]
	ds_read_b128 v[152:155], v99 offset:17248
	s_waitcnt lgkmcnt(7)
	v_mfma_f32_32x32x16_bf16 v[2:17], v[156:159], v[42:45], v[2:17]
	ds_read_b128 v[156:159], v99 offset:17280
	s_waitcnt lgkmcnt(7)
	v_mfma_f32_32x32x16_bf16 v[2:17], v[160:163], v[46:49], v[2:17]
	ds_read_b128 v[160:163], v99 offset:17312
	s_waitcnt lgkmcnt(7)
	v_mfma_f32_32x32x16_bf16 v[2:17], v[164:167], v[50:53], v[2:17]
	ds_read_b128 v[164:167], v99 offset:17344
	s_waitcnt lgkmcnt(7)
	v_mfma_f32_32x32x16_bf16 v[2:17], v[168:171], v[54:57], v[2:17]
	ds_read_b128 v[168:171], v99 offset:17376
	s_waitcnt lgkmcnt(7)
	v_mfma_f32_32x32x16_bf16 v[2:17], v[140:143], v[58:61], v[2:17]
	s_waitcnt lgkmcnt(6)
	v_mfma_f32_32x32x16_bf16 v[2:17], v[144:147], v[62:65], v[2:17]
	s_waitcnt lgkmcnt(5)
	v_mfma_f32_32x32x16_bf16 v[2:17], v[148:151], v[66:69], v[2:17]
	s_waitcnt lgkmcnt(4)
	v_mfma_f32_32x32x16_bf16 v[2:17], v[152:155], v[70:73], v[2:17]
	s_waitcnt lgkmcnt(3)
	v_mfma_f32_32x32x16_bf16 v[2:17], v[156:159], v[74:77], v[2:17]
	s_waitcnt lgkmcnt(2)
	v_mfma_f32_32x32x16_bf16 v[2:17], v[160:163], v[78:81], v[2:17]
	s_waitcnt lgkmcnt(1)
	v_mfma_f32_32x32x16_bf16 v[2:17], v[164:167], v[86:89], v[2:17]
	s_waitcnt lgkmcnt(0)
	v_mfma_f32_32x32x16_bf16 v[2:17], v[168:171], v[82:85], v[2:17]
	s_nop 11
	v_pk_mul_f32 v[2:3], v[98:99], v[2:3] op_sel_hi:[0,1]
	v_pk_mul_f32 v[4:5], v[98:99], v[4:5] op_sel_hi:[0,1]
	v_pk_mul_f32 v[6:7], v[98:99], v[6:7] op_sel_hi:[0,1]
	v_pk_mul_f32 v[8:9], v[98:99], v[8:9] op_sel_hi:[0,1]
	v_pk_mul_f32 v[10:11], v[98:99], v[10:11] op_sel_hi:[0,1]
	v_pk_mul_f32 v[12:13], v[98:99], v[12:13] op_sel_hi:[0,1]
	v_pk_mul_f32 v[14:15], v[98:99], v[14:15] op_sel_hi:[0,1]
	v_pk_mul_f32 v[16:17], v[98:99], v[16:17] op_sel_hi:[0,1]
	v_cvt_pk_bf16_f32 v2, v2, v3
	v_cvt_pk_bf16_f32 v3, v4, v5
	v_cvt_pk_bf16_f32 v4, v6, v7
	v_cvt_pk_bf16_f32 v5, v8, v9
	v_cvt_pk_bf16_f32 v6, v10, v11
	v_cvt_pk_bf16_f32 v7, v12, v13
	v_cvt_pk_bf16_f32 v8, v14, v15
	v_cvt_pk_bf16_f32 v9, v16, v17
	ds_write2_b64 v100, v[2:3], v[4:5] offset0:8 offset1:10
	ds_write2_b64 v100, v[6:7], v[8:9] offset0:12 offset1:14
	ds_read_b128 v[2:5], v0 offset:34816
	ds_read_b128 v[6:9], v0 offset:35968
	ds_read_b128 v[10:13], v0 offset:37120
	ds_read_b128 v[14:17], v0 offset:38272
	s_waitcnt lgkmcnt(3)
	global_store_dwordx4 v[26:27], v[2:5], off offset:384
	s_waitcnt lgkmcnt(2)
	global_store_dwordx4 v[28:29], v[6:9], off offset:384
	s_waitcnt lgkmcnt(1)
	global_store_dwordx4 v[30:31], v[10:13], off offset:384
	s_waitcnt lgkmcnt(0)
	global_store_dwordx4 v[32:33], v[14:17], off offset:384
	s_branch .LBB0_585
